# GEMM epilogues (gate, relu2, both residual, kv up-proj): the 4-lane row-scale / sum-of-squares reductions use v_permlane16_swap + v_permlane32_swap instead of two ds_bpermute round trips
# baseline (speedup 1.0000x reference)
; __device__ __forceinline__ unsigned pk_bf16(float lo, float hi) { typedef float f2_t __attribute__((ext_vector_type(2))); typedef __bf16 b2_t __attribute__((ext_vector_type(2))); f2_t v = {lo, hi}; b2_t b = __builtin_convertvector(v, b2_t); return __builtin_bit_cast(unsigned, b); }
; __device__ __forceinline__ int vperm16(int s) { return (s & 3) + ((s >> 3) & 1) * 4 + ((s >> 2) & 1) * 8; }
;     __device__ __forceinline__ void storeT(bf16_t* vt  , int d0, int s, f32x4 v0, f32x4 v1) const {
;         const int pos = (s & ~15) + vperm16(s & 15);
; #pragma unroll
;         for (int e = 0; e < 4; ++e) { vt[(size_t)(d0 + e) * SEQ + pos] = (bf16_t)(pk_bf16(v0[e], 0.f) & 0xffffu); vt[(size_t)(d0 + 4 + e) * SEQ + pos] = (bf16_t)(pk_bf16(v1[e], 0.f) & 0xffffu); }
;     }
;     __device__ __forceinline__ void operator()(const f32x4 (&acc)[2][2][4][2], const Unit& u, int wr, int wc, int fr, int fq) const {
;     ...
;             for (int ai = 0; ai < 2; ++ai)
; #pragma unroll
;                 for (int m = 0; m < 4; ++m) {
;                     float t = (part[ai][m][0] + part[ai][m][1]) + (part[ai][m][2] + part[ai][m][3]);
;                     t += __shfl_xor(t, 16); t += __shfl_xor(t, 32);
;                     rsc[ai][m] = __builtin_amdgcn_rsqf(t * rs_inv + EPS);
;                 }
.LBB0_531:
	s_or_b64 exec, exec, s[0:1]
	v_pk_add_f32 v[138:139], v[182:183], v[138:139]
	s_mov_b64 s[0:1], -1
	v_add_f32_e32 v0, v138, v139
	v_mov_b32_e32 v138, v0
	s_nop 1
	v_permlane16_swap_b32 v0, v138
	s_nop 1
	s_and_b64 vcc, exec, s[10:11]
	s_waitcnt lgkmcnt(0)
	v_add_f32_e32 v0, v0, v138
	v_mov_b32_e32 v138, v0
	s_nop 1
	v_permlane32_swap_b32 v0, v138
	s_nop 1
	s_waitcnt lgkmcnt(0)
	v_add_f32_e32 v0, v0, v138
	v_fmamk_f32 v0, v0, 0x3b800000, v195
	v_rsq_f32_e32 v138, v0
	s_waitcnt vmcnt(0)
	v_add_f32_e32 v0, v130, v131
	v_add_f32_e32 v130, v132, v133
	v_add_f32_e32 v0, v0, v130
	v_mov_b32_e32 v130, v0
	s_nop 1
	v_permlane16_swap_b32 v0, v130
	s_nop 1
	v_pk_mul_f32 v[128:129], v[128:129], v[138:139] op_sel_hi:[1,0]
	v_pk_mul_f32 v[126:127], v[126:127], v[138:139] op_sel_hi:[1,0]
	v_pk_mul_f32 v[132:133], v[124:125], v[138:139] op_sel_hi:[1,0]
	s_waitcnt lgkmcnt(0)
	v_add_f32_e32 v181, v0, v130
	v_add_f32_e32 v0, v144, v145
	v_add_f32_e32 v130, v146, v147
	v_add_f32_e32 v0, v0, v130
	v_mov_b32_e32 v130, v0
	s_nop 1
	v_permlane16_swap_b32 v0, v130
	s_nop 1
	v_mov_b32_e32 v182, v181
	s_nop 1
	v_permlane32_swap_b32 v181, v182
	s_nop 1
	s_waitcnt lgkmcnt(1)
	v_add_f32_e32 v177, v0, v130
	v_add_f32_e32 v0, v134, v135
	v_add_f32_e32 v130, v136, v137
	v_add_f32_e32 v0, v0, v130
	v_mov_b32_e32 v130, v0
	s_nop 1
	v_permlane16_swap_b32 v0, v130
	s_nop 1
	v_mov_b32_e32 v179, v177
	s_nop 1
	v_permlane32_swap_b32 v177, v179
	s_nop 1
	v_pk_mul_f32 v[134:135], v[122:123], v[138:139] op_sel_hi:[1,0]
	v_lshlrev_b32_e32 v122, 1, v170
	s_waitcnt lgkmcnt(1)
	v_add_f32_e32 v146, v0, v130
	v_add_f32_e32 v0, v148, v149
	v_add_f32_e32 v130, v150, v151
	v_add_f32_e32 v0, v0, v130
	v_mov_b32_e32 v130, v0
	s_nop 1
	v_permlane16_swap_b32 v0, v130
	s_nop 1
	v_lshrrev_b32_e32 v148, 19, v175
	v_mov_b32_e32 v147, v146
	s_nop 1
	v_permlane32_swap_b32 v146, v147
	s_nop 1
	s_waitcnt lgkmcnt(1)
	v_add_f32_e32 v144, v0, v130
	v_add_f32_e32 v0, v140, v141
	v_add_f32_e32 v130, v142, v143
	v_add_f32_e32 v0, v0, v130
	v_mov_b32_e32 v130, v0
	s_nop 1
	v_permlane16_swap_b32 v0, v130
	s_nop 1
	v_mov_b32_e32 v145, v144
	s_nop 1
	v_permlane32_swap_b32 v144, v145
	s_nop 1
	s_waitcnt lgkmcnt(1)
	v_add_f32_e32 v142, v0, v130
	v_add_f32_e32 v0, v156, v157
	v_add_f32_e32 v130, v158, v159
	v_add_f32_e32 v0, v0, v130
	v_mov_b32_e32 v130, v0
	s_nop 1
	v_permlane16_swap_b32 v0, v130
	s_nop 1
	v_mov_b32_e32 v143, v142
	s_nop 1
	v_permlane32_swap_b32 v142, v143
	s_nop 1
	s_waitcnt lgkmcnt(1)
	v_add_f32_e32 v140, v0, v130
	v_add_f32_e32 v0, v152, v153
	v_add_f32_e32 v130, v154, v155
	v_add_f32_e32 v0, v0, v130
	v_mov_b32_e32 v130, v0
	s_nop 1
	v_permlane16_swap_b32 v0, v130
	s_nop 1
	v_mov_b32_e32 v141, v140
	s_nop 1
	v_permlane32_swap_b32 v140, v141
	s_nop 1
	s_waitcnt lgkmcnt(1)
	v_add_f32_e32 v136, v0, v130
	v_add_u32_e32 v0, v174, v148
	v_ashrrev_i32_e32 v0, 13, v0
	v_mul_i32_i24_e32 v130, 0x2000, v0
	v_mov_b32_e32 v137, v136
	s_nop 1
	v_permlane32_swap_b32 v136, v137
	s_nop 1
	v_sub_u32_e32 v130, v174, v130
	v_lshlrev_b32_e32 v149, 3, v0
	v_lshrrev_b32_e32 v0, 1, v130
	v_lshlrev_b32_e32 v131, 1, v130
	v_and_b32_e32 v0, 4, v0
	v_and_b32_e32 v131, 8, v131
	v_and_b32_e32 v130, 0xffffffc3, v130
	v_or3_b32 v130, v0, v130, v131
	v_ashrrev_i32_e32 v131, 31, v130
	s_cbranch_vccz .LBB0_533
	s_lshl_b32 s46, s67, 1
	v_add_u32_e32 v124, s46, v149
	v_ashrrev_i32_e32 v125, 31, v124
	v_lshlrev_b64 v[124:125], 20, v[124:125]
	v_lshl_add_u64 v[124:125], s[34:35], 0, v[124:125]
	v_lshl_add_u64 v[124:125], v[130:131], 1, v[124:125]
	v_mov_b32_e32 v123, v1
	v_cvt_pk_bf16_f32 v0, v126, s0
	v_lshl_add_u64 v[124:125], v[124:125], 0, v[122:123]
	global_store_short v[124:125], v0, off
	v_cvt_pk_bf16_f32 v0, v134, s0
	s_mov_b32 s0, 0x10000
	v_add_co_u32_e32 v150, vcc, s0, v124
	s_nop 1
	v_addc_co_u32_e32 v151, vcc, 0, v125, vcc
	global_store_short v[150:151], v0, off
	v_cvt_pk_bf16_f32 v0, v127, s0
	s_movk_i32 s0, 0x4000
	v_add_co_u32_e32 v150, vcc, s0, v124
	s_nop 1
	v_addc_co_u32_e32 v151, vcc, 0, v125, vcc
	global_store_short v[150:151], v0, off
	v_cvt_pk_bf16_f32 v0, v135, s0
	s_mov_b32 s0, 0x14000
	v_add_co_u32_e32 v150, vcc, s0, v124
	s_nop 1
	v_addc_co_u32_e32 v151, vcc, 0, v125, vcc
	global_store_short v[150:151], v0, off
	v_cvt_pk_bf16_f32 v0, v128, s0
	s_mov_b32 s0, 0x8000
	v_add_co_u32_e32 v150, vcc, s0, v124
	s_nop 1
	v_addc_co_u32_e32 v151, vcc, 0, v125, vcc
	global_store_short v[150:151], v0, off
	v_cvt_pk_bf16_f32 v0, v132, s0
	s_mov_b32 s0, 0x18000
	v_add_co_u32_e32 v150, vcc, s0, v124
	s_nop 1
	v_addc_co_u32_e32 v151, vcc, 0, v125, vcc
	global_store_short v[150:151], v0, off
	v_add_co_u32_e32 v150, vcc, 0xc000, v124
	v_cvt_pk_bf16_f32 v0, v129, s0
	s_nop 0
	v_addc_co_u32_e32 v151, vcc, 0, v125, vcc
	v_add_co_u32_e32 v124, vcc, 0x1c000, v124
	global_store_short v[150:151], v0, off
	v_cvt_pk_bf16_f32 v0, v133, s0
	v_addc_co_u32_e32 v125, vcc, 0, v125, vcc
	global_store_short v[124:125], v0, off
	s_mov_b64 s[0:1], 0

;     __device__ __forceinline__ void operator()(const f32x4 (&acc)[2][2][4][2], const Unit& u, int wr, int wc, int fr, int fq) const {
;     ...
;         if (rs_n > 0) {
;             f32x4 part[2][4];
; #pragma unroll
;             for (int ai = 0; ai < 2; ++ai)
; #pragma unroll
;                 for (int m = 0; m < 4; ++m) {
;                     part[ai][m] = (f32x4){0.f, 0.f, 0.f, 0.f};
;                     if (4 * fq < rs_n) part[ai][m] = *(const f32x4*)(rs + (size_t)(row0 + ai * HALF + m * 16) * rs_ld + rs_off + 4 * fq);
;                 }
; #pragma unroll
;             for (int ai = 0; ai < 2; ++ai)
; #pragma unroll
;                 for (int m = 0; m < 4; ++m) {
;                     float t = (part[ai][m][0] + part[ai][m][1]) + (part[ai][m][2] + part[ai][m][3]);
;                     t += __shfl_xor(t, 16); t += __shfl_xor(t, 32);
;                     rsc[ai][m] = __builtin_amdgcn_rsqf(t * rs_inv + EPS);
;                 }
;     ...
;                 if (mode == EP_GATE) {
;                     const size_t off = (size_t)row * DM + u.pn * 128 + wc * 32 + 8 * fq;
;                     const f32x4 a0 = acc[ai][0][m][0] * rs1, a1 = acc[ai][0][m][1] * rs1, b0 = acc[ai][1][m][0] * rs1, b1 = acc[ai][1][m][1] * rs1;
.LBB0_1082:
	v_lshl_add_u32 v210, s22, 8, v171
	v_ashrrev_i32_e32 v211, 31, v210
	v_lshlrev_b64 v[130:131], 6, v[210:211]
	v_lshl_add_u64 v[130:131], v[172:173], 0, v[130:131]
	global_load_dwordx4 v[130:133], v[130:131], off
	v_or_b32_e32 v206, 16, v210
	v_ashrrev_i32_e32 v207, 31, v206
	v_lshlrev_b64 v[134:135], 6, v[206:207]
	v_lshl_add_u64 v[134:135], v[172:173], 0, v[134:135]
	global_load_dwordx4 v[134:137], v[134:135], off
	v_or_b32_e32 v204, 32, v210
	v_ashrrev_i32_e32 v205, 31, v204
	v_lshlrev_b64 v[138:139], 6, v[204:205]
	v_lshl_add_u64 v[138:139], v[172:173], 0, v[138:139]
	global_load_dwordx4 v[138:141], v[138:139], off
	v_or_b32_e32 v198, 48, v210
	v_ashrrev_i32_e32 v199, 31, v198
	v_lshlrev_b64 v[142:143], 6, v[198:199]
	v_lshl_add_u64 v[142:143], v[172:173], 0, v[142:143]
	global_load_dwordx4 v[142:145], v[142:143], off
	v_add_u32_e32 v188, 0x80, v210
	v_ashrrev_i32_e32 v189, 31, v188
	v_lshlrev_b64 v[146:147], 6, v[188:189]
	v_lshl_add_u64 v[146:147], v[172:173], 0, v[146:147]
	global_load_dwordx4 v[146:149], v[146:147], off
	v_add_u32_e32 v184, 0x90, v210
	v_ashrrev_i32_e32 v185, 31, v184
	v_lshlrev_b64 v[150:151], 6, v[184:185]
	v_lshl_add_u64 v[150:151], v[172:173], 0, v[150:151]
	global_load_dwordx4 v[150:153], v[150:151], off
	v_add_u32_e32 v182, 0xa0, v210
	v_ashrrev_i32_e32 v183, 31, v182
	v_lshlrev_b64 v[154:155], 6, v[182:183]
	v_lshl_add_u64 v[154:155], v[172:173], 0, v[154:155]
	global_load_dwordx4 v[154:157], v[154:155], off
	v_add_u32_e32 v178, 0xb0, v210
	v_ashrrev_i32_e32 v179, 31, v178
	v_lshlrev_b64 v[158:159], 6, v[178:179]
	v_lshl_add_u64 v[158:159], v[172:173], 0, v[158:159]
	global_load_dwordx4 v[158:161], v[158:159], off
	s_lshl_b32 s4, s21, 7
	s_ashr_i32 s5, s4, 31
	v_mov_b32_e32 v201, s5
	v_or_b32_e32 v200, s4, v170
	s_lshl_b64 s[4:5], s[4:5], 1
	s_andn2_b64 vcc, exec, s[36:37]
	s_waitcnt vmcnt(0)
	v_mov_b32_e32 v190, v131
	v_mov_b32_e32 v191, v132
	v_mov_b32_e32 v131, v133
	v_pk_add_f32 v[130:131], v[190:191], v[130:131]
	v_mov_b32_e32 v132, v195
	v_add_f32_e32 v130, v130, v131
	v_mov_b32_e32 v131, v130
	s_nop 1
	v_permlane16_swap_b32 v130, v131
	s_nop 1
	s_waitcnt lgkmcnt(0)
	v_add_f32_e32 v130, v130, v131
	v_mov_b32_e32 v131, v130
	s_nop 1
	v_permlane32_swap_b32 v130, v131
	s_nop 1
	s_waitcnt lgkmcnt(0)
	v_add_f32_e32 v130, v130, v131
	v_fmamk_f32 v130, v130, 0x3a800000, v195
	v_rsq_f32_e32 v214, v130
	v_mov_b32_e32 v130, v135
	v_mov_b32_e32 v131, v136
	v_mov_b32_e32 v135, v137
	v_pk_add_f32 v[130:131], v[130:131], v[134:135]
	v_pk_mul_f32 v[118:119], v[118:119], v[214:215] op_sel_hi:[1,0]
	v_add_f32_e32 v130, v130, v131
	v_mov_b32_e32 v131, v130
	s_nop 1
	v_permlane16_swap_b32 v130, v131
	s_nop 1
	v_pk_mul_f32 v[126:127], v[126:127], v[214:215] op_sel_hi:[1,0]
	v_mul_f32_e32 v118, 0xbfb8aa3b, v118
	v_mul_f32_e32 v119, 0xbfb8aa3b, v119
	v_mul_f32_e32 v126, 0xbfb8aa3b, v126
	s_waitcnt lgkmcnt(0)
	v_add_f32_e32 v130, v130, v131
	v_mov_b32_e32 v131, v130
	s_nop 1
	v_permlane32_swap_b32 v130, v131
	s_nop 1
	v_exp_f32_e32 v118, v118
	v_mul_f32_e32 v127, 0xbfb8aa3b, v127
	v_exp_f32_e32 v119, v119
	v_exp_f32_e32 v126, v126
	s_waitcnt lgkmcnt(0)
	v_add_f32_e32 v130, v130, v131
	v_fmamk_f32 v130, v130, 0x3a800000, v132
	v_rsq_f32_e32 v212, v130
	v_mov_b32_e32 v130, v139
	v_mov_b32_e32 v131, v140
	v_mov_b32_e32 v139, v141
	v_pk_add_f32 v[130:131], v[130:131], v[138:139]
	v_exp_f32_e32 v127, v127
	v_add_f32_e32 v130, v130, v131
	v_mov_b32_e32 v131, v130
	s_nop 1
	v_permlane16_swap_b32 v130, v131
	s_nop 1
	v_add_f32_e32 v118, 1.0, v118
	v_add_f32_e32 v119, 1.0, v119
	v_add_f32_e32 v126, 1.0, v126
	v_rcp_f32_e32 v118, v118
	s_waitcnt lgkmcnt(0)
	v_add_f32_e32 v130, v130, v131
	v_mov_b32_e32 v131, v130
	s_nop 1
	v_permlane32_swap_b32 v130, v131
	s_nop 1
	v_add_f32_e32 v127, 1.0, v127
	v_rcp_f32_e32 v119, v119
	v_rcp_f32_e32 v126, v126
	v_rcp_f32_e32 v127, v127
	s_waitcnt lgkmcnt(0)
	v_add_f32_e32 v130, v130, v131
	v_fmamk_f32 v130, v130, 0x3a800000, v132
	v_rsq_f32_e32 v208, v130
	v_mov_b32_e32 v130, v143
	v_mov_b32_e32 v131, v144
	v_mov_b32_e32 v143, v145
	v_pk_add_f32 v[130:131], v[130:131], v[142:143]
	v_pk_mul_f32 v[120:121], v[120:121], v[214:215] op_sel_hi:[1,0]
	v_add_f32_e32 v130, v130, v131
	v_mov_b32_e32 v131, v130
	s_nop 1
	v_permlane16_swap_b32 v130, v131
	s_nop 1
	v_pk_mul_f32 v[128:129], v[128:129], v[214:215] op_sel_hi:[1,0]
	v_mul_f32_e32 v120, 0xbfb8aa3b, v120
	v_mul_f32_e32 v121, 0xbfb8aa3b, v121
	v_pk_mul_f32 v[114:115], v[114:115], v[214:215] op_sel_hi:[1,0]
	s_waitcnt lgkmcnt(0)
	v_add_f32_e32 v130, v130, v131
	v_mov_b32_e32 v131, v130
	s_nop 1
	v_permlane32_swap_b32 v130, v131
	s_nop 1
	v_exp_f32_e32 v120, v120
	v_exp_f32_e32 v121, v121
	v_pk_mul_f32 v[122:123], v[122:123], v[214:215] op_sel_hi:[1,0]
	v_mul_f32_e32 v114, 0xbfb8aa3b, v114
	s_waitcnt lgkmcnt(0)
	v_add_f32_e32 v130, v130, v131
	v_fmamk_f32 v130, v130, 0x3a800000, v132
	v_rsq_f32_e32 v202, v130
	v_mov_b32_e32 v130, v147
	v_mov_b32_e32 v131, v148
	v_mov_b32_e32 v147, v149
	v_pk_add_f32 v[130:131], v[130:131], v[146:147]
	v_mul_f32_e32 v115, 0xbfb8aa3b, v115
	v_add_f32_e32 v130, v130, v131
	v_mov_b32_e32 v131, v130
	s_nop 1
	v_permlane16_swap_b32 v130, v131
	s_nop 1
	v_mul_f32_e32 v122, 0xbfb8aa3b, v122
	v_exp_f32_e32 v114, v114
	v_mul_f32_e32 v123, 0xbfb8aa3b, v123
	v_exp_f32_e32 v115, v115
	s_waitcnt lgkmcnt(0)
	v_add_f32_e32 v130, v130, v131
	v_mov_b32_e32 v131, v130
	s_nop 1
	v_permlane32_swap_b32 v130, v131
	s_nop 1
	v_exp_f32_e32 v122, v122
	v_exp_f32_e32 v123, v123
	v_add_f32_e32 v120, 1.0, v120
	v_add_f32_e32 v121, 1.0, v121
	s_waitcnt lgkmcnt(0)
;     __device__ __forceinline__ void operator()(const f32x4 (&acc)[2][2][4][2], const Unit& u, int wr, int wc, int fr, int fq) const {
;     ...
;             for (int ai = 0; ai < 2; ++ai)
; #pragma unroll
;                 for (int m = 0; m < 4; ++m) {
;                     float t = (part[ai][m][0] + part[ai][m][1]) + (part[ai][m][2] + part[ai][m][3]);
;                     t += __shfl_xor(t, 16); t += __shfl_xor(t, 32);
;                     rsc[ai][m] = __builtin_amdgcn_rsqf(t * rs_inv + EPS);
;                 }
;     ...
;                 if (mode == EP_GATE) {
; #pragma unroll
;                     for (int m = 0; m < 4; ++m) { const size_t off = (size_t)(row0 + ai * HALF + m * 16) * DM + u.pn * 128 + wc * 32 + 8 * fq; yall[ai][m][0] = *(const u32x4*)(Y1 + off); yall[ai][m][1] = *(const u32x4*)(Y2 + off); }
	v_add_f32_e32 v130, v130, v131
	v_fmamk_f32 v130, v130, 0x3a800000, v132
	v_rsq_f32_e32 v196, v130
	v_mov_b32_e32 v130, v151
	v_mov_b32_e32 v131, v152
	v_mov_b32_e32 v151, v153
	v_pk_add_f32 v[130:131], v[130:131], v[150:151]
	v_rcp_f32_e32 v120, v120
	v_add_f32_e32 v130, v130, v131
	v_mov_b32_e32 v131, v130
	s_nop 1
	v_permlane16_swap_b32 v130, v131
	s_nop 1
	v_rcp_f32_e32 v121, v121
	v_add_f32_e32 v114, 1.0, v114
	v_add_f32_e32 v115, 1.0, v115
	v_add_f32_e32 v122, 1.0, v122
	s_waitcnt lgkmcnt(0)
	v_add_f32_e32 v130, v130, v131
	v_mov_b32_e32 v131, v130
	s_nop 1
	v_permlane32_swap_b32 v130, v131
	s_nop 1
	v_rcp_f32_e32 v114, v114
	v_add_f32_e32 v123, 1.0, v123
	v_rcp_f32_e32 v115, v115
	v_rcp_f32_e32 v122, v122
	s_waitcnt lgkmcnt(0)
	v_add_f32_e32 v130, v130, v131
	v_fmamk_f32 v130, v130, 0x3a800000, v132
	v_rsq_f32_e32 v190, v130
	v_mov_b32_e32 v130, v155
	v_mov_b32_e32 v131, v156
	v_mov_b32_e32 v155, v157
	v_pk_add_f32 v[130:131], v[130:131], v[154:155]
	v_rcp_f32_e32 v123, v123
	v_add_f32_e32 v130, v130, v131
	v_mov_b32_e32 v131, v130
	s_nop 1
	v_permlane16_swap_b32 v130, v131
	s_nop 1
	v_pk_mul_f32 v[116:117], v[116:117], v[214:215] op_sel_hi:[1,0]
	v_pk_mul_f32 v[124:125], v[124:125], v[214:215] op_sel_hi:[1,0]
	v_mul_f32_e32 v117, 0xbfb8aa3b, v117
	v_exp_f32_e32 v117, v117
	s_waitcnt lgkmcnt(0)
	v_add_f32_e32 v130, v130, v131
	v_mov_b32_e32 v131, v130
	s_nop 1
	v_permlane32_swap_b32 v130, v131
	s_nop 1
	v_pk_mul_f32 v[102:103], v[102:103], v[212:213] op_sel_hi:[1,0]
	v_add_f32_e32 v117, 1.0, v117
	v_rcp_f32_e32 v117, v117
	v_pk_mul_f32 v[110:111], v[110:111], v[212:213] op_sel_hi:[1,0]
	s_waitcnt lgkmcnt(0)
	v_add_f32_e32 v130, v130, v131
	v_fmamk_f32 v130, v130, 0x3a800000, v132
	v_rsq_f32_e32 v186, v130
	v_mov_b32_e32 v130, v159
	v_mov_b32_e32 v131, v160
	v_mov_b32_e32 v159, v161
	v_pk_add_f32 v[130:131], v[130:131], v[158:159]
	v_mul_f32_e32 v102, 0xbfb8aa3b, v102
	v_add_f32_e32 v130, v130, v131
	v_mov_b32_e32 v131, v130
	s_nop 1
	v_permlane16_swap_b32 v130, v131
	s_nop 1
	v_mul_f32_e32 v103, 0xbfb8aa3b, v103
	v_mul_f32_e32 v110, 0xbfb8aa3b, v110
	v_exp_f32_e32 v102, v102
	v_mul_f32_e32 v111, 0xbfb8aa3b, v111
	s_waitcnt lgkmcnt(0)
	v_add_f32_e32 v130, v130, v131
	v_mov_b32_e32 v131, v130
	s_nop 1
	v_permlane32_swap_b32 v130, v131
	s_nop 1
	v_exp_f32_e32 v103, v103
	v_exp_f32_e32 v110, v110
	v_exp_f32_e32 v111, v111
	v_add_f32_e32 v102, 1.0, v102
	s_waitcnt lgkmcnt(0)
	v_add_f32_e32 v130, v130, v131
	v_fmamk_f32 v130, v130, 0x3a800000, v132
	v_rsq_f32_e32 v180, v130
	v_lshlrev_b64 v[130:131], 10, v[210:211]
	v_lshl_add_u64 v[130:131], v[130:131], 0, v[200:201]
	v_lshlrev_b64 v[130:131], 1, v[130:131]
	v_lshl_add_u64 v[132:133], s[38:39], 0, v[130:131]
	v_lshl_add_u64 v[130:131], s[42:43], 0, v[130:131]
	global_load_dwordx4 v[154:157], v[132:133], off
	global_load_dwordx4 v[158:161], v[130:131], off
	v_lshlrev_b64 v[130:131], 10, v[206:207]
	v_lshl_add_u64 v[130:131], v[130:131], 0, v[200:201]
	v_lshlrev_b64 v[130:131], 1, v[130:131]
	v_lshl_add_u64 v[132:133], s[38:39], 0, v[130:131]
	v_lshl_add_u64 v[130:131], s[42:43], 0, v[130:131]
	global_load_dwordx4 v[146:149], v[132:133], off
	global_load_dwordx4 v[150:153], v[130:131], off
	v_lshlrev_b64 v[130:131], 10, v[204:205]
	v_lshl_add_u64 v[130:131], v[130:131], 0, v[200:201]
	v_lshlrev_b64 v[130:131], 1, v[130:131]
	v_lshl_add_u64 v[132:133], s[38:39], 0, v[130:131]
	v_lshl_add_u64 v[130:131], s[42:43], 0, v[130:131]
	global_load_dwordx4 v[138:141], v[132:133], off
	global_load_dwordx4 v[142:145], v[130:131], off
	v_lshlrev_b64 v[130:131], 10, v[198:199]
	v_lshl_add_u64 v[130:131], v[130:131], 0, v[200:201]
	v_lshlrev_b64 v[134:135], 1, v[130:131]
	v_lshl_add_u64 v[130:131], s[38:39], 0, v[134:135]
	v_lshl_add_u64 v[134:135], s[42:43], 0, v[134:135]
	global_load_dwordx4 v[130:133], v[130:131], off
	v_add_f32_e32 v103, 1.0, v103
	global_load_dwordx4 v[134:137], v[134:135], off
	v_add_f32_e32 v110, 1.0, v110
	v_rcp_f32_e32 v102, v102
	v_add_f32_e32 v111, 1.0, v111
	v_rcp_f32_e32 v103, v103
	v_rcp_f32_e32 v110, v110
	v_rcp_f32_e32 v111, v111
	v_pk_mul_f32 v[104:105], v[104:105], v[212:213] op_sel_hi:[1,0]
	v_pk_mul_f32 v[112:113], v[112:113], v[212:213] op_sel_hi:[1,0]
	v_mul_f32_e32 v104, 0xbfb8aa3b, v104
	v_mul_f32_e32 v105, 0xbfb8aa3b, v105
	v_pk_mul_f32 v[98:99], v[98:99], v[212:213] op_sel_hi:[1,0]
	v_exp_f32_e32 v104, v104
	v_exp_f32_e32 v105, v105
	v_pk_mul_f32 v[106:107], v[106:107], v[212:213] op_sel_hi:[1,0]
	v_mul_f32_e32 v98, 0xbfb8aa3b, v98
	v_mul_f32_e32 v99, 0xbfb8aa3b, v99
	v_mul_f32_e32 v106, 0xbfb8aa3b, v106
	v_exp_f32_e32 v98, v98
	v_mul_f32_e32 v107, 0xbfb8aa3b, v107
	v_exp_f32_e32 v99, v99
	v_exp_f32_e32 v106, v106
	v_exp_f32_e32 v107, v107
	v_add_f32_e32 v104, 1.0, v104
	v_add_f32_e32 v105, 1.0, v105
	v_rcp_f32_e32 v104, v104
	v_rcp_f32_e32 v105, v105
	v_add_f32_e32 v98, 1.0, v98
	v_add_f32_e32 v99, 1.0, v99
	v_add_f32_e32 v106, 1.0, v106
	v_rcp_f32_e32 v98, v98
	v_add_f32_e32 v107, 1.0, v107
	v_rcp_f32_e32 v99, v99
	v_rcp_f32_e32 v106, v106
	v_rcp_f32_e32 v107, v107
	v_pk_mul_f32 v[100:101], v[100:101], v[212:213] op_sel_hi:[1,0]
	v_pk_mul_f32 v[108:109], v[108:109], v[212:213] op_sel_hi:[1,0]
	v_mul_f32_e32 v101, 0xbfb8aa3b, v101
	v_exp_f32_e32 v101, v101
	v_pk_mul_f32 v[86:87], v[86:87], v[208:209] op_sel_hi:[1,0]
	v_pk_mul_f32 v[94:95], v[94:95], v[208:209] op_sel_hi:[1,0]
	v_mul_f32_e32 v86, 0xbfb8aa3b, v86
	v_add_f32_e32 v101, 1.0, v101
	v_rcp_f32_e32 v101, v101
	v_mul_f32_e32 v87, 0xbfb8aa3b, v87
	v_mul_f32_e32 v94, 0xbfb8aa3b, v94
	v_exp_f32_e32 v86, v86
	v_mul_f32_e32 v95, 0xbfb8aa3b, v95
	v_exp_f32_e32 v87, v87
	v_exp_f32_e32 v94, v94
	v_exp_f32_e32 v95, v95
	v_add_f32_e32 v86, 1.0, v86
	v_add_f32_e32 v87, 1.0, v87
	v_add_f32_e32 v94, 1.0, v94
	v_rcp_f32_e32 v86, v86
	v_add_f32_e32 v95, 1.0, v95
	v_rcp_f32_e32 v87, v87
	s_waitcnt vmcnt(7)
; __device__ __forceinline__ float sigmoidf_(float x) { return __builtin_amdgcn_rcpf(1.0f + __builtin_amdgcn_exp2f(-1.4426950408889634f * x)); }
;     __device__ __forceinline__ void operator()(const f32x4 (&acc)[2][2][4][2], const Unit& u, int wr, int wc, int fr, int fq) const {
;     ...
;                 if (mode == EP_GATE) {
;                     const size_t off = (size_t)row * DM + u.pn * 128 + wc * 32 + 8 * fq;
;                     const f32x4 a0 = acc[ai][0][m][0] * rs1, a1 = acc[ai][0][m][1] * rs1, b0 = acc[ai][1][m][0] * rs1, b1 = acc[ai][1][m][1] * rs1;
;                     const u32x4 y1 = yall[ai][m][0], y2 = yall[ai][m][1];
;                     f32x4 r0, r1;
;                     r0[0] = sigmoidf_(a0[0]) * bf_lo(y1.x) + sigmoidf_(b0[0]) * bf_lo(y2.x); r0[1] = sigmoidf_(a0[1]) * bf_hi(y1.x) + sigmoidf_(b0[1]) * bf_hi(y2.x);
;                     r0[2] = sigmoidf_(a0[2]) * bf_lo(y1.y) + sigmoidf_(b0[2]) * bf_lo(y2.y); r0[3] = sigmoidf_(a0[3]) * bf_hi(y1.y) + sigmoidf_(b0[3]) * bf_hi(y2.y);
;                     r1[0] = sigmoidf_(a1[0]) * bf_lo(y1.z) + sigmoidf_(b1[0]) * bf_lo(y2.z); r1[1] = sigmoidf_(a1[1]) * bf_hi(y1.z) + sigmoidf_(b1[1]) * bf_hi(y2.z);
;                     r1[2] = sigmoidf_(a1[2]) * bf_lo(y1.w) + sigmoidf_(b1[2]) * bf_lo(y2.w); r1[3] = sigmoidf_(a1[3]) * bf_hi(y1.w) + sigmoidf_(b1[3]) * bf_hi(y2.w);
;                     store8(O + off, r0, r1);
	v_lshlrev_b32_e32 v192, 16, v154
	s_waitcnt vmcnt(6)
	v_lshlrev_b32_e32 v222, 16, v158
	v_and_b32_e32 v223, 0xffff0000, v158
	v_and_b32_e32 v193, 0xffff0000, v154
	v_pk_mul_f32 v[118:119], v[118:119], v[222:223]
	v_lshlrev_b32_e32 v154, 16, v159
	v_pk_fma_f32 v[118:119], v[126:127], v[192:193], v[118:119]
	v_mul_f32_e32 v126, 0xbfb8aa3b, v128
	v_mul_f32_e32 v127, 0xbfb8aa3b, v129
	v_exp_f32_e32 v126, v126
	v_exp_f32_e32 v127, v127
	v_lshlrev_b32_e32 v128, 16, v155
	v_and_b32_e32 v129, 0xffff0000, v155
	v_add_f32_e32 v126, 1.0, v126
	v_add_f32_e32 v127, 1.0, v127
	v_rcp_f32_e32 v126, v126
	v_rcp_f32_e32 v127, v127
	v_and_b32_e32 v155, 0xffff0000, v159
	v_pk_mul_f32 v[120:121], v[120:121], v[154:155]
	v_rcp_f32_e32 v94, v94
	v_pk_fma_f32 v[120:121], v[126:127], v[128:129], v[120:121]
	v_lshlrev_b32_e32 v128, 16, v160
	v_and_b32_e32 v129, 0xffff0000, v160
	v_lshlrev_b32_e32 v126, 16, v156
	v_and_b32_e32 v127, 0xffff0000, v156
	v_pk_mul_f32 v[114:115], v[114:115], v[128:129]
	v_rcp_f32_e32 v95, v95
	v_pk_fma_f32 v[122:123], v[122:123], v[126:127], v[114:115]
	v_mul_f32_e32 v115, 0xbfb8aa3b, v116
	v_exp_f32_e32 v115, v115
	v_mul_f32_e32 v114, 0xbfb8aa3b, v124
	v_exp_f32_e32 v114, v114
	v_lshlrev_b32_e32 v126, 16, v161
	v_add_f32_e32 v115, 1.0, v115
	v_rcp_f32_e32 v116, v115
	v_mul_f32_e32 v115, 0xbfb8aa3b, v125
	v_exp_f32_e32 v115, v115
	v_add_f32_e32 v114, 1.0, v114
	v_rcp_f32_e32 v114, v114
	v_and_b32_e32 v127, 0xffff0000, v161
	v_add_f32_e32 v115, 1.0, v115
	v_rcp_f32_e32 v115, v115
	v_lshlrev_b32_e32 v124, 16, v157
	v_and_b32_e32 v125, 0xffff0000, v157
	v_pk_mul_f32 v[116:117], v[116:117], v[126:127]
	v_pk_mul_f32 v[88:89], v[88:89], v[208:209] op_sel_hi:[1,0]
	v_pk_fma_f32 v[124:125], v[114:115], v[124:125], v[116:117]
	v_lshlrev_b64 v[114:115], 11, v[210:211]
	v_lshl_add_u64 v[114:115], s[40:41], 0, v[114:115]
	v_lshl_add_u64 v[114:115], v[114:115], 0, s[4:5]
	v_lshl_add_u64 v[114:115], v[114:115], 0, s[12:13]
	v_lshl_add_u64 v[126:127], v[114:115], 0, v[0:1]
	v_cvt_pk_bf16_f32 v114, v118, v119
	v_cvt_pk_bf16_f32 v115, v120, v121
	v_cvt_pk_bf16_f32 v116, v122, v123
	v_cvt_pk_bf16_f32 v117, v124, v125
	global_store_dwordx4 v[126:127], v[114:117], off
	v_pk_mul_f32 v[96:97], v[96:97], v[208:209] op_sel_hi:[1,0]
	v_mul_f32_e32 v88, 0xbfb8aa3b, v88
	s_waitcnt vmcnt(5)
	v_lshlrev_b32_e32 v116, 16, v150
	v_and_b32_e32 v117, 0xffff0000, v150
	v_lshlrev_b32_e32 v114, 16, v146
	v_and_b32_e32 v115, 0xffff0000, v146
	v_pk_mul_f32 v[102:103], v[102:103], v[116:117]
	v_mul_f32_e32 v89, 0xbfb8aa3b, v89
	v_pk_fma_f32 v[102:103], v[110:111], v[114:115], v[102:103]
	v_mul_f32_e32 v110, 0xbfb8aa3b, v112
	v_mul_f32_e32 v111, 0xbfb8aa3b, v113
	v_exp_f32_e32 v110, v110
	v_exp_f32_e32 v111, v111
	v_lshlrev_b32_e32 v114, 16, v151
	v_and_b32_e32 v115, 0xffff0000, v151
	v_add_f32_e32 v110, 1.0, v110
	v_add_f32_e32 v111, 1.0, v111
	v_rcp_f32_e32 v110, v110
	v_rcp_f32_e32 v111, v111
	v_lshlrev_b32_e32 v112, 16, v147
	v_and_b32_e32 v113, 0xffff0000, v147
	v_pk_mul_f32 v[104:105], v[104:105], v[114:115]
	v_pk_mul_f32 v[82:83], v[82:83], v[208:209] op_sel_hi:[1,0]
	v_pk_fma_f32 v[104:105], v[110:111], v[112:113], v[104:105]
	v_lshlrev_b32_e32 v112, 16, v152
	v_and_b32_e32 v113, 0xffff0000, v152
	v_lshlrev_b32_e32 v110, 16, v148
	v_and_b32_e32 v111, 0xffff0000, v148
	v_pk_mul_f32 v[98:99], v[98:99], v[112:113]
	v_exp_f32_e32 v88, v88
	v_pk_fma_f32 v[106:107], v[106:107], v[110:111], v[98:99]
	v_mul_f32_e32 v99, 0xbfb8aa3b, v100
	v_exp_f32_e32 v99, v99
	v_mul_f32_e32 v98, 0xbfb8aa3b, v108
	v_exp_f32_e32 v98, v98
	v_lshlrev_b32_e32 v110, 16, v153
	v_add_f32_e32 v99, 1.0, v99
	v_rcp_f32_e32 v100, v99
	v_mul_f32_e32 v99, 0xbfb8aa3b, v109
	v_exp_f32_e32 v99, v99
	v_add_f32_e32 v98, 1.0, v98
	v_rcp_f32_e32 v98, v98
	v_and_b32_e32 v111, 0xffff0000, v153
	v_add_f32_e32 v99, 1.0, v99
	v_rcp_f32_e32 v99, v99
	v_lshlrev_b32_e32 v108, 16, v149
	v_and_b32_e32 v109, 0xffff0000, v149
	v_pk_mul_f32 v[100:101], v[100:101], v[110:111]
	v_exp_f32_e32 v89, v89
	v_pk_fma_f32 v[108:109], v[98:99], v[108:109], v[100:101]
	v_lshlrev_b64 v[98:99], 11, v[206:207]
	v_lshl_add_u64 v[98:99], s[40:41], 0, v[98:99]
	v_lshl_add_u64 v[98:99], v[98:99], 0, s[4:5]
	v_lshl_add_u64 v[98:99], v[98:99], 0, s[12:13]
	v_lshl_add_u64 v[110:111], v[98:99], 0, v[0:1]
	v_cvt_pk_bf16_f32 v98, v102, v103
	v_cvt_pk_bf16_f32 v99, v104, v105
	v_cvt_pk_bf16_f32 v100, v106, v107
	v_cvt_pk_bf16_f32 v101, v108, v109
	s_waitcnt vmcnt(3)
; __device__ __forceinline__ float sigmoidf_(float x) { return __builtin_amdgcn_rcpf(1.0f + __builtin_amdgcn_exp2f(-1.4426950408889634f * x)); }
;     __device__ __forceinline__ void operator()(const f32x4 (&acc)[2][2][4][2], const Unit& u, int wr, int wc, int fr, int fq) const {
;     ...
;                 if (mode == EP_GATE) {
;                     const size_t off = (size_t)row * DM + u.pn * 128 + wc * 32 + 8 * fq;
;                     const f32x4 a0 = acc[ai][0][m][0] * rs1, a1 = acc[ai][0][m][1] * rs1, b0 = acc[ai][1][m][0] * rs1, b1 = acc[ai][1][m][1] * rs1;
;                     const u32x4 y1 = yall[ai][m][0], y2 = yall[ai][m][1];
;                     f32x4 r0, r1;
;                     r0[0] = sigmoidf_(a0[0]) * bf_lo(y1.x) + sigmoidf_(b0[0]) * bf_lo(y2.x); r0[1] = sigmoidf_(a0[1]) * bf_hi(y1.x) + sigmoidf_(b0[1]) * bf_hi(y2.x);
;                     r0[2] = sigmoidf_(a0[2]) * bf_lo(y1.y) + sigmoidf_(b0[2]) * bf_lo(y2.y); r0[3] = sigmoidf_(a0[3]) * bf_hi(y1.y) + sigmoidf_(b0[3]) * bf_hi(y2.y);
;                     r1[0] = sigmoidf_(a1[0]) * bf_lo(y1.z) + sigmoidf_(b1[0]) * bf_lo(y2.z); r1[1] = sigmoidf_(a1[1]) * bf_hi(y1.z) + sigmoidf_(b1[1]) * bf_hi(y2.z);
;                     r1[2] = sigmoidf_(a1[2]) * bf_lo(y1.w) + sigmoidf_(b1[2]) * bf_lo(y2.w); r1[3] = sigmoidf_(a1[3]) * bf_hi(y1.w) + sigmoidf_(b1[3]) * bf_hi(y2.w);
;                     store8(O + off, r0, r1);
	v_lshlrev_b32_e32 v102, 16, v142
	v_and_b32_e32 v103, 0xffff0000, v142
	global_store_dwordx4 v[110:111], v[98:101], off
	v_pk_mul_f32 v[86:87], v[86:87], v[102:103]
	v_pk_mul_f32 v[90:91], v[90:91], v[208:209] op_sel_hi:[1,0]
	v_lshlrev_b32_e32 v100, 16, v138
	v_and_b32_e32 v101, 0xffff0000, v138
	v_pk_fma_f32 v[86:87], v[94:95], v[100:101], v[86:87]
	v_mul_f32_e32 v94, 0xbfb8aa3b, v96
	v_mul_f32_e32 v95, 0xbfb8aa3b, v97
	v_exp_f32_e32 v94, v94
	v_exp_f32_e32 v95, v95
	v_mul_f32_e32 v82, 0xbfb8aa3b, v82
	v_mul_f32_e32 v83, 0xbfb8aa3b, v83
	v_mul_f32_e32 v90, 0xbfb8aa3b, v90
	v_exp_f32_e32 v82, v82
	v_mul_f32_e32 v91, 0xbfb8aa3b, v91
	v_exp_f32_e32 v83, v83
	v_exp_f32_e32 v90, v90
	v_exp_f32_e32 v91, v91
	v_add_f32_e32 v88, 1.0, v88
	v_add_f32_e32 v89, 1.0, v89
	v_add_f32_e32 v94, 1.0, v94
	v_rcp_f32_e32 v88, v88
	v_add_f32_e32 v95, 1.0, v95
	v_rcp_f32_e32 v89, v89
	v_rcp_f32_e32 v94, v94
	v_rcp_f32_e32 v95, v95
	v_add_f32_e32 v82, 1.0, v82
	v_add_f32_e32 v83, 1.0, v83
	v_add_f32_e32 v90, 1.0, v90
	v_rcp_f32_e32 v82, v82
	v_add_f32_e32 v91, 1.0, v91
	v_rcp_f32_e32 v83, v83
	v_lshlrev_b32_e32 v100, 16, v143
	v_and_b32_e32 v101, 0xffff0000, v143
	v_rcp_f32_e32 v90, v90
	v_rcp_f32_e32 v91, v91
	v_lshlrev_b32_e32 v96, 16, v139
	v_and_b32_e32 v97, 0xffff0000, v139
	v_pk_mul_f32 v[88:89], v[88:89], v[100:101]
	v_pk_mul_f32 v[84:85], v[84:85], v[208:209] op_sel_hi:[1,0]
	v_pk_fma_f32 v[88:89], v[94:95], v[96:97], v[88:89]
	v_lshlrev_b32_e32 v96, 16, v144
	v_and_b32_e32 v97, 0xffff0000, v144
	v_lshlrev_b32_e32 v94, 16, v140
	v_and_b32_e32 v95, 0xffff0000, v140
	v_pk_mul_f32 v[82:83], v[82:83], v[96:97]
	v_pk_mul_f32 v[92:93], v[92:93], v[208:209] op_sel_hi:[1,0]
	v_pk_fma_f32 v[90:91], v[90:91], v[94:95], v[82:83]
	v_mul_f32_e32 v83, 0xbfb8aa3b, v84
	v_exp_f32_e32 v83, v83
	v_mul_f32_e32 v85, 0xbfb8aa3b, v85
	v_mul_f32_e32 v82, 0xbfb8aa3b, v92
	v_exp_f32_e32 v85, v85
	v_add_f32_e32 v83, 1.0, v83
	v_rcp_f32_e32 v84, v83
	v_mul_f32_e32 v83, 0xbfb8aa3b, v93
	v_exp_f32_e32 v82, v82
	v_exp_f32_e32 v83, v83
	v_add_f32_e32 v85, 1.0, v85
	v_pk_mul_f32 v[70:71], v[70:71], v[202:203] op_sel_hi:[1,0]
	v_add_f32_e32 v82, 1.0, v82
	v_add_f32_e32 v83, 1.0, v83
	v_rcp_f32_e32 v85, v85
	v_pk_mul_f32 v[78:79], v[78:79], v[202:203] op_sel_hi:[1,0]
	v_mul_f32_e32 v70, 0xbfb8aa3b, v70
	v_mul_f32_e32 v71, 0xbfb8aa3b, v71
	v_rcp_f32_e32 v82, v82
	v_rcp_f32_e32 v83, v83
	v_mul_f32_e32 v78, 0xbfb8aa3b, v78
	v_exp_f32_e32 v70, v70
	v_mul_f32_e32 v79, 0xbfb8aa3b, v79
	v_exp_f32_e32 v71, v71
	v_exp_f32_e32 v78, v78
	v_exp_f32_e32 v79, v79
	v_lshlrev_b32_e32 v94, 16, v145
	v_and_b32_e32 v95, 0xffff0000, v145
	v_lshlrev_b64 v[98:99], 11, v[204:205]
	v_lshlrev_b32_e32 v92, 16, v141
	v_and_b32_e32 v93, 0xffff0000, v141
	v_pk_mul_f32 v[84:85], v[84:85], v[94:95]
	v_add_f32_e32 v70, 1.0, v70
	v_pk_fma_f32 v[92:93], v[82:83], v[92:93], v[84:85]
	v_lshl_add_u64 v[82:83], s[40:41], 0, v[98:99]
	v_add_f32_e32 v71, 1.0, v71
	v_lshl_add_u64 v[82:83], v[82:83], 0, s[4:5]
	v_add_f32_e32 v78, 1.0, v78
	v_rcp_f32_e32 v70, v70
	v_add_f32_e32 v79, 1.0, v79
	v_rcp_f32_e32 v71, v71
	v_lshl_add_u64 v[82:83], v[82:83], 0, s[12:13]
	v_rcp_f32_e32 v78, v78
	v_rcp_f32_e32 v79, v79
	v_lshl_add_u64 v[94:95], v[82:83], 0, v[0:1]
	v_cvt_pk_bf16_f32 v82, v86, v87
	v_cvt_pk_bf16_f32 v83, v88, v89
	v_cvt_pk_bf16_f32 v84, v90, v91
	v_cvt_pk_bf16_f32 v85, v92, v93
	global_store_dwordx4 v[94:95], v[82:85], off
	v_pk_mul_f32 v[72:73], v[72:73], v[202:203] op_sel_hi:[1,0]
	v_pk_mul_f32 v[80:81], v[80:81], v[202:203] op_sel_hi:[1,0]
	s_waitcnt vmcnt(3)
	v_lshlrev_b32_e32 v84, 16, v134
	v_and_b32_e32 v85, 0xffff0000, v134
	v_lshlrev_b32_e32 v82, 16, v130
	v_and_b32_e32 v83, 0xffff0000, v130
	v_pk_mul_f32 v[70:71], v[70:71], v[84:85]
	v_mul_f32_e32 v72, 0xbfb8aa3b, v72
	v_mul_f32_e32 v73, 0xbfb8aa3b, v73
	v_pk_mul_f32 v[66:67], v[66:67], v[202:203] op_sel_hi:[1,0]
	v_pk_fma_f32 v[70:71], v[78:79], v[82:83], v[70:71]
	v_mul_f32_e32 v78, 0xbfb8aa3b, v80
	v_exp_f32_e32 v72, v72
	v_mul_f32_e32 v79, 0xbfb8aa3b, v81
	v_exp_f32_e32 v73, v73
	v_pk_mul_f32 v[74:75], v[74:75], v[202:203] op_sel_hi:[1,0]
	v_exp_f32_e32 v78, v78
	v_exp_f32_e32 v79, v79
	v_mul_f32_e32 v66, 0xbfb8aa3b, v66
	v_mul_f32_e32 v67, 0xbfb8aa3b, v67
	v_mul_f32_e32 v74, 0xbfb8aa3b, v74
	v_exp_f32_e32 v66, v66
	v_mul_f32_e32 v75, 0xbfb8aa3b, v75
	v_exp_f32_e32 v67, v67
	v_exp_f32_e32 v74, v74
	v_exp_f32_e32 v75, v75
	v_add_f32_e32 v72, 1.0, v72
	v_add_f32_e32 v73, 1.0, v73
	v_add_f32_e32 v78, 1.0, v78
	v_rcp_f32_e32 v72, v72
	v_add_f32_e32 v79, 1.0, v79
	v_rcp_f32_e32 v73, v73
	v_rcp_f32_e32 v78, v78
	v_rcp_f32_e32 v79, v79
	v_add_f32_e32 v66, 1.0, v66
	v_add_f32_e32 v67, 1.0, v67
	v_add_f32_e32 v74, 1.0, v74
	v_rcp_f32_e32 v66, v66
	v_add_f32_e32 v75, 1.0, v75
	v_rcp_f32_e32 v67, v67
	v_lshlrev_b32_e32 v82, 16, v135
	v_and_b32_e32 v83, 0xffff0000, v135
	v_rcp_f32_e32 v74, v74
	v_rcp_f32_e32 v75, v75
	v_lshlrev_b32_e32 v80, 16, v131
	v_and_b32_e32 v81, 0xffff0000, v131
	v_pk_mul_f32 v[72:73], v[72:73], v[82:83]
	v_pk_mul_f32 v[68:69], v[68:69], v[202:203] op_sel_hi:[1,0]
	v_pk_fma_f32 v[72:73], v[78:79], v[80:81], v[72:73]
	v_lshlrev_b32_e32 v80, 16, v136
	v_and_b32_e32 v81, 0xffff0000, v136
	v_lshlrev_b32_e32 v78, 16, v132
	v_and_b32_e32 v79, 0xffff0000, v132
	v_pk_mul_f32 v[66:67], v[66:67], v[80:81]
	v_pk_mul_f32 v[76:77], v[76:77], v[202:203] op_sel_hi:[1,0]
	v_pk_fma_f32 v[74:75], v[74:75], v[78:79], v[66:67]
	v_mul_f32_e32 v67, 0xbfb8aa3b, v68
	v_exp_f32_e32 v67, v67
	v_mul_f32_e32 v69, 0xbfb8aa3b, v69
	v_mul_f32_e32 v66, 0xbfb8aa3b, v76
	v_exp_f32_e32 v69, v69
	v_add_f32_e32 v67, 1.0, v67
	v_rcp_f32_e32 v68, v67
	v_mul_f32_e32 v67, 0xbfb8aa3b, v77
; __device__ __forceinline__ float sigmoidf_(float x) { return __builtin_amdgcn_rcpf(1.0f + __builtin_amdgcn_exp2f(-1.4426950408889634f * x)); }
;     __device__ __forceinline__ void operator()(const f32x4 (&acc)[2][2][4][2], const Unit& u, int wr, int wc, int fr, int fq) const {
;     ...
;                 if (mode == EP_GATE) {
;                     const size_t off = (size_t)row * DM + u.pn * 128 + wc * 32 + 8 * fq;
;                     const f32x4 a0 = acc[ai][0][m][0] * rs1, a1 = acc[ai][0][m][1] * rs1, b0 = acc[ai][1][m][0] * rs1, b1 = acc[ai][1][m][1] * rs1;
;                     const u32x4 y1 = yall[ai][m][0], y2 = yall[ai][m][1];
;                     f32x4 r0, r1;
;                     r0[0] = sigmoidf_(a0[0]) * bf_lo(y1.x) + sigmoidf_(b0[0]) * bf_lo(y2.x); r0[1] = sigmoidf_(a0[1]) * bf_hi(y1.x) + sigmoidf_(b0[1]) * bf_hi(y2.x);
;                     r0[2] = sigmoidf_(a0[2]) * bf_lo(y1.y) + sigmoidf_(b0[2]) * bf_lo(y2.y); r0[3] = sigmoidf_(a0[3]) * bf_hi(y1.y) + sigmoidf_(b0[3]) * bf_hi(y2.y);
;                     r1[0] = sigmoidf_(a1[0]) * bf_lo(y1.z) + sigmoidf_(b1[0]) * bf_lo(y2.z); r1[1] = sigmoidf_(a1[1]) * bf_hi(y1.z) + sigmoidf_(b1[1]) * bf_hi(y2.z);
;                     r1[2] = sigmoidf_(a1[2]) * bf_lo(y1.w) + sigmoidf_(b1[2]) * bf_lo(y2.w); r1[3] = sigmoidf_(a1[3]) * bf_hi(y1.w) + sigmoidf_(b1[3]) * bf_hi(y2.w);
;                     store8(O + off, r0, r1);
	v_exp_f32_e32 v66, v66
	v_exp_f32_e32 v67, v67
	v_add_f32_e32 v69, 1.0, v69
	v_rcp_f32_e32 v69, v69
	v_add_f32_e32 v66, 1.0, v66
	v_add_f32_e32 v67, 1.0, v67
	v_rcp_f32_e32 v66, v66
	v_rcp_f32_e32 v67, v67
	v_lshlrev_b32_e32 v78, 16, v137
	v_and_b32_e32 v79, 0xffff0000, v137
	v_lshlrev_b32_e32 v76, 16, v133
	v_and_b32_e32 v77, 0xffff0000, v133
	v_pk_mul_f32 v[68:69], v[68:69], v[78:79]
	v_pk_mul_f32 v[54:55], v[54:55], v[196:197] op_sel_hi:[1,0]
	v_pk_fma_f32 v[76:77], v[66:67], v[76:77], v[68:69]
	v_lshlrev_b64 v[66:67], 11, v[198:199]
	v_lshl_add_u64 v[66:67], s[40:41], 0, v[66:67]
	v_lshl_add_u64 v[66:67], v[66:67], 0, s[4:5]
	v_lshl_add_u64 v[66:67], v[66:67], 0, s[12:13]
	v_lshl_add_u64 v[78:79], v[66:67], 0, v[0:1]
	v_cvt_pk_bf16_f32 v66, v70, v71
	v_cvt_pk_bf16_f32 v67, v72, v73
	v_cvt_pk_bf16_f32 v68, v74, v75
	v_cvt_pk_bf16_f32 v69, v76, v77
	global_store_dwordx4 v[78:79], v[66:69], off
	v_pk_mul_f32 v[62:63], v[62:63], v[196:197] op_sel_hi:[1,0]
	v_mul_f32_e32 v54, 0xbfb8aa3b, v54
	v_lshlrev_b64 v[66:67], 10, v[188:189]
	v_lshl_add_u64 v[66:67], v[66:67], 0, v[200:201]
	v_lshlrev_b64 v[66:67], 1, v[66:67]
	v_lshl_add_u64 v[68:69], s[38:39], 0, v[66:67]
	v_lshl_add_u64 v[66:67], s[42:43], 0, v[66:67]
	global_load_dwordx4 v[94:97], v[68:69], off
	global_load_dwordx4 v[90:93], v[66:67], off
	v_lshlrev_b64 v[66:67], 10, v[184:185]
	v_lshl_add_u64 v[66:67], v[66:67], 0, v[200:201]
	v_lshlrev_b64 v[66:67], 1, v[66:67]
	v_lshl_add_u64 v[68:69], s[38:39], 0, v[66:67]
	v_lshl_add_u64 v[66:67], s[42:43], 0, v[66:67]
	global_load_dwordx4 v[82:85], v[68:69], off
	global_load_dwordx4 v[86:89], v[66:67], off
	v_lshlrev_b64 v[66:67], 10, v[182:183]
	v_lshl_add_u64 v[66:67], v[66:67], 0, v[200:201]
	v_lshlrev_b64 v[66:67], 1, v[66:67]
	v_lshl_add_u64 v[68:69], s[38:39], 0, v[66:67]
	v_lshl_add_u64 v[66:67], s[42:43], 0, v[66:67]
	global_load_dwordx4 v[74:77], v[68:69], off
	global_load_dwordx4 v[78:81], v[66:67], off
	v_mul_f32_e32 v55, 0xbfb8aa3b, v55
	v_mul_f32_e32 v62, 0xbfb8aa3b, v62
	v_exp_f32_e32 v54, v54
	v_mul_f32_e32 v63, 0xbfb8aa3b, v63
	v_exp_f32_e32 v55, v55
	v_exp_f32_e32 v62, v62
	v_exp_f32_e32 v63, v63
	v_add_f32_e32 v54, 1.0, v54
	v_add_f32_e32 v55, 1.0, v55
	v_add_f32_e32 v62, 1.0, v62
	v_rcp_f32_e32 v54, v54
	v_add_f32_e32 v63, 1.0, v63
	v_rcp_f32_e32 v55, v55
	v_rcp_f32_e32 v62, v62
	v_rcp_f32_e32 v63, v63
	v_pk_mul_f32 v[56:57], v[56:57], v[196:197] op_sel_hi:[1,0]
	v_pk_mul_f32 v[64:65], v[64:65], v[196:197] op_sel_hi:[1,0]
	v_mul_f32_e32 v56, 0xbfb8aa3b, v56
	v_mul_f32_e32 v57, 0xbfb8aa3b, v57
	v_pk_mul_f32 v[50:51], v[50:51], v[196:197] op_sel_hi:[1,0]
	v_exp_f32_e32 v56, v56
	v_exp_f32_e32 v57, v57
	v_pk_mul_f32 v[58:59], v[58:59], v[196:197] op_sel_hi:[1,0]
	v_mul_f32_e32 v50, 0xbfb8aa3b, v50
	v_mul_f32_e32 v51, 0xbfb8aa3b, v51
	v_mul_f32_e32 v58, 0xbfb8aa3b, v58
	v_exp_f32_e32 v50, v50
	v_mul_f32_e32 v59, 0xbfb8aa3b, v59
	v_exp_f32_e32 v51, v51
	v_exp_f32_e32 v58, v58
	v_exp_f32_e32 v59, v59
	v_add_f32_e32 v56, 1.0, v56
	v_add_f32_e32 v57, 1.0, v57
	v_rcp_f32_e32 v56, v56
	v_rcp_f32_e32 v57, v57
	v_add_f32_e32 v50, 1.0, v50
	v_add_f32_e32 v51, 1.0, v51
	v_add_f32_e32 v58, 1.0, v58
	v_rcp_f32_e32 v50, v50
	v_add_f32_e32 v59, 1.0, v59
	v_rcp_f32_e32 v51, v51
	v_rcp_f32_e32 v58, v58
	v_rcp_f32_e32 v59, v59
	v_pk_mul_f32 v[52:53], v[52:53], v[196:197] op_sel_hi:[1,0]
	v_lshlrev_b64 v[66:67], 10, v[178:179]
	v_pk_mul_f32 v[60:61], v[60:61], v[196:197] op_sel_hi:[1,0]
	v_mul_f32_e32 v53, 0xbfb8aa3b, v53
	v_lshl_add_u64 v[66:67], v[66:67], 0, v[200:201]
	v_exp_f32_e32 v53, v53
	v_lshlrev_b64 v[70:71], 1, v[66:67]
	v_lshl_add_u64 v[66:67], s[38:39], 0, v[70:71]
	v_lshl_add_u64 v[70:71], s[42:43], 0, v[70:71]
	global_load_dwordx4 v[66:69], v[66:67], off
	v_add_f32_e32 v53, 1.0, v53
	global_load_dwordx4 v[70:73], v[70:71], off
	v_rcp_f32_e32 v53, v53
	v_pk_mul_f32 v[38:39], v[38:39], v[190:191] op_sel_hi:[1,0]
	v_pk_mul_f32 v[46:47], v[46:47], v[190:191] op_sel_hi:[1,0]
	v_mul_f32_e32 v38, 0xbfb8aa3b, v38
	v_mul_f32_e32 v39, 0xbfb8aa3b, v39
	v_mul_f32_e32 v46, 0xbfb8aa3b, v46
	v_exp_f32_e32 v38, v38
	v_mul_f32_e32 v47, 0xbfb8aa3b, v47
	v_exp_f32_e32 v39, v39
	s_waitcnt vmcnt(7)
	v_lshlrev_b32_e32 v98, 16, v94
	s_waitcnt vmcnt(6)
	v_lshlrev_b32_e32 v100, 16, v90
	v_and_b32_e32 v101, 0xffff0000, v90
	v_and_b32_e32 v99, 0xffff0000, v94
	v_pk_mul_f32 v[54:55], v[54:55], v[100:101]
	v_lshlrev_b32_e32 v90, 16, v91
	v_pk_fma_f32 v[54:55], v[62:63], v[98:99], v[54:55]
	v_mul_f32_e32 v62, 0xbfb8aa3b, v64
	v_mul_f32_e32 v63, 0xbfb8aa3b, v65
	v_exp_f32_e32 v62, v62
	v_exp_f32_e32 v63, v63
	v_and_b32_e32 v91, 0xffff0000, v91
	v_lshlrev_b32_e32 v64, 16, v95
	v_add_f32_e32 v62, 1.0, v62
	v_add_f32_e32 v63, 1.0, v63
	v_rcp_f32_e32 v62, v62
	v_rcp_f32_e32 v63, v63
	v_and_b32_e32 v65, 0xffff0000, v95
	v_pk_mul_f32 v[56:57], v[56:57], v[90:91]
	v_exp_f32_e32 v46, v46
	v_pk_fma_f32 v[56:57], v[62:63], v[64:65], v[56:57]
	v_lshlrev_b32_e32 v64, 16, v92
	v_and_b32_e32 v65, 0xffff0000, v92
	v_lshlrev_b32_e32 v62, 16, v96
	v_and_b32_e32 v63, 0xffff0000, v96
	v_pk_mul_f32 v[50:51], v[50:51], v[64:65]
	v_exp_f32_e32 v47, v47
	v_pk_fma_f32 v[58:59], v[58:59], v[62:63], v[50:51]
	v_mul_f32_e32 v51, 0xbfb8aa3b, v52
	v_exp_f32_e32 v51, v51
	v_mul_f32_e32 v50, 0xbfb8aa3b, v60
	v_exp_f32_e32 v50, v50
	v_lshlrev_b32_e32 v62, 16, v93
	v_add_f32_e32 v51, 1.0, v51
	v_rcp_f32_e32 v52, v51
	v_mul_f32_e32 v51, 0xbfb8aa3b, v61
	v_exp_f32_e32 v51, v51
	v_add_f32_e32 v50, 1.0, v50
	v_rcp_f32_e32 v50, v50
	v_and_b32_e32 v63, 0xffff0000, v93
	v_add_f32_e32 v51, 1.0, v51
	v_rcp_f32_e32 v51, v51
	v_lshlrev_b32_e32 v60, 16, v97
	v_and_b32_e32 v61, 0xffff0000, v97
	v_pk_mul_f32 v[52:53], v[52:53], v[62:63]
	v_add_f32_e32 v38, 1.0, v38
	v_pk_fma_f32 v[60:61], v[50:51], v[60:61], v[52:53]
	v_lshlrev_b64 v[50:51], 11, v[188:189]
	v_lshl_add_u64 v[50:51], s[40:41], 0, v[50:51]
	v_add_f32_e32 v39, 1.0, v39
	v_lshl_add_u64 v[50:51], v[50:51], 0, s[4:5]
	v_add_f32_e32 v46, 1.0, v46
	v_rcp_f32_e32 v38, v38
	v_add_f32_e32 v47, 1.0, v47
	v_rcp_f32_e32 v39, v39
	v_lshl_add_u64 v[50:51], v[50:51], 0, s[12:13]
	v_rcp_f32_e32 v46, v46
	v_rcp_f32_e32 v47, v47
	v_lshl_add_u64 v[62:63], v[50:51], 0, v[0:1]
	v_cvt_pk_bf16_f32 v50, v54, v55
	v_cvt_pk_bf16_f32 v51, v56, v57
	v_cvt_pk_bf16_f32 v52, v58, v59
	v_cvt_pk_bf16_f32 v53, v60, v61
	global_store_dwordx4 v[62:63], v[50:53], off
	v_pk_mul_f32 v[40:41], v[40:41], v[190:191] op_sel_hi:[1,0]
	v_pk_mul_f32 v[48:49], v[48:49], v[190:191] op_sel_hi:[1,0]
	s_waitcnt vmcnt(5)
; __device__ __forceinline__ float sigmoidf_(float x) { return __builtin_amdgcn_rcpf(1.0f + __builtin_amdgcn_exp2f(-1.4426950408889634f * x)); }
;     __device__ __forceinline__ void operator()(const f32x4 (&acc)[2][2][4][2], const Unit& u, int wr, int wc, int fr, int fq) const {
;     ...
;                 if (mode == EP_GATE) {
;                     const size_t off = (size_t)row * DM + u.pn * 128 + wc * 32 + 8 * fq;
;                     const f32x4 a0 = acc[ai][0][m][0] * rs1, a1 = acc[ai][0][m][1] * rs1, b0 = acc[ai][1][m][0] * rs1, b1 = acc[ai][1][m][1] * rs1;
;                     const u32x4 y1 = yall[ai][m][0], y2 = yall[ai][m][1];
;                     f32x4 r0, r1;
;                     r0[0] = sigmoidf_(a0[0]) * bf_lo(y1.x) + sigmoidf_(b0[0]) * bf_lo(y2.x); r0[1] = sigmoidf_(a0[1]) * bf_hi(y1.x) + sigmoidf_(b0[1]) * bf_hi(y2.x);
;                     r0[2] = sigmoidf_(a0[2]) * bf_lo(y1.y) + sigmoidf_(b0[2]) * bf_lo(y2.y); r0[3] = sigmoidf_(a0[3]) * bf_hi(y1.y) + sigmoidf_(b0[3]) * bf_hi(y2.y);
;                     r1[0] = sigmoidf_(a1[0]) * bf_lo(y1.z) + sigmoidf_(b1[0]) * bf_lo(y2.z); r1[1] = sigmoidf_(a1[1]) * bf_hi(y1.z) + sigmoidf_(b1[1]) * bf_hi(y2.z);
;                     r1[2] = sigmoidf_(a1[2]) * bf_lo(y1.w) + sigmoidf_(b1[2]) * bf_lo(y2.w); r1[3] = sigmoidf_(a1[3]) * bf_hi(y1.w) + sigmoidf_(b1[3]) * bf_hi(y2.w);
;                     store8(O + off, r0, r1);
	v_lshlrev_b32_e32 v52, 16, v86
	v_and_b32_e32 v53, 0xffff0000, v86
	v_lshlrev_b32_e32 v50, 16, v82
	v_and_b32_e32 v51, 0xffff0000, v82
	v_pk_mul_f32 v[38:39], v[38:39], v[52:53]
	v_mul_f32_e32 v40, 0xbfb8aa3b, v40
	v_mul_f32_e32 v41, 0xbfb8aa3b, v41
	v_pk_mul_f32 v[34:35], v[34:35], v[190:191] op_sel_hi:[1,0]
	v_pk_fma_f32 v[38:39], v[46:47], v[50:51], v[38:39]
	v_mul_f32_e32 v46, 0xbfb8aa3b, v48
	v_exp_f32_e32 v40, v40
	v_mul_f32_e32 v47, 0xbfb8aa3b, v49
	v_exp_f32_e32 v41, v41
	v_pk_mul_f32 v[42:43], v[42:43], v[190:191] op_sel_hi:[1,0]
	v_exp_f32_e32 v46, v46
	v_exp_f32_e32 v47, v47
	v_mul_f32_e32 v34, 0xbfb8aa3b, v34
	v_mul_f32_e32 v35, 0xbfb8aa3b, v35
	v_mul_f32_e32 v42, 0xbfb8aa3b, v42
	v_exp_f32_e32 v34, v34
	v_mul_f32_e32 v43, 0xbfb8aa3b, v43
	v_exp_f32_e32 v35, v35
	v_exp_f32_e32 v42, v42
	v_exp_f32_e32 v43, v43
	v_add_f32_e32 v40, 1.0, v40
	v_add_f32_e32 v41, 1.0, v41
	v_add_f32_e32 v46, 1.0, v46
	v_rcp_f32_e32 v40, v40
	v_add_f32_e32 v47, 1.0, v47
	v_rcp_f32_e32 v41, v41
	v_rcp_f32_e32 v46, v46
	v_rcp_f32_e32 v47, v47
	v_add_f32_e32 v34, 1.0, v34
	v_add_f32_e32 v35, 1.0, v35
	v_add_f32_e32 v42, 1.0, v42
	v_rcp_f32_e32 v34, v34
	v_add_f32_e32 v43, 1.0, v43
	v_rcp_f32_e32 v35, v35
	v_lshlrev_b32_e32 v50, 16, v87
	v_and_b32_e32 v51, 0xffff0000, v87
	v_rcp_f32_e32 v42, v42
	v_rcp_f32_e32 v43, v43
	v_lshlrev_b32_e32 v48, 16, v83
	v_and_b32_e32 v49, 0xffff0000, v83
	v_pk_mul_f32 v[40:41], v[40:41], v[50:51]
	v_pk_mul_f32 v[36:37], v[36:37], v[190:191] op_sel_hi:[1,0]
	v_pk_fma_f32 v[40:41], v[46:47], v[48:49], v[40:41]
	v_lshlrev_b32_e32 v48, 16, v88
	v_and_b32_e32 v49, 0xffff0000, v88
	v_lshlrev_b32_e32 v46, 16, v84
	v_and_b32_e32 v47, 0xffff0000, v84
	v_pk_mul_f32 v[34:35], v[34:35], v[48:49]
	v_pk_mul_f32 v[44:45], v[44:45], v[190:191] op_sel_hi:[1,0]
	v_pk_fma_f32 v[42:43], v[42:43], v[46:47], v[34:35]
	v_mul_f32_e32 v35, 0xbfb8aa3b, v36
	v_exp_f32_e32 v35, v35
	v_mul_f32_e32 v37, 0xbfb8aa3b, v37
	v_mul_f32_e32 v34, 0xbfb8aa3b, v44
	v_exp_f32_e32 v37, v37
	v_add_f32_e32 v35, 1.0, v35
	v_rcp_f32_e32 v36, v35
	v_mul_f32_e32 v35, 0xbfb8aa3b, v45
	v_exp_f32_e32 v34, v34
	v_exp_f32_e32 v35, v35
	v_add_f32_e32 v37, 1.0, v37
	v_pk_mul_f32 v[22:23], v[22:23], v[186:187] op_sel_hi:[1,0]
	v_add_f32_e32 v34, 1.0, v34
	v_add_f32_e32 v35, 1.0, v35
	v_rcp_f32_e32 v37, v37
	v_pk_mul_f32 v[30:31], v[30:31], v[186:187] op_sel_hi:[1,0]
	v_mul_f32_e32 v22, 0xbfb8aa3b, v22
	v_mul_f32_e32 v23, 0xbfb8aa3b, v23
	v_rcp_f32_e32 v34, v34
	v_rcp_f32_e32 v35, v35
	v_mul_f32_e32 v30, 0xbfb8aa3b, v30
	v_exp_f32_e32 v22, v22
	v_mul_f32_e32 v31, 0xbfb8aa3b, v31
	v_exp_f32_e32 v23, v23
	v_exp_f32_e32 v30, v30
	v_exp_f32_e32 v31, v31
	v_lshlrev_b32_e32 v46, 16, v89
	v_and_b32_e32 v47, 0xffff0000, v89
	v_lshlrev_b32_e32 v44, 16, v85
	v_and_b32_e32 v45, 0xffff0000, v85
	v_pk_mul_f32 v[36:37], v[36:37], v[46:47]
	v_add_f32_e32 v22, 1.0, v22
	v_pk_fma_f32 v[44:45], v[34:35], v[44:45], v[36:37]
	v_lshlrev_b64 v[34:35], 11, v[184:185]
	v_add_f32_e32 v23, 1.0, v23
	v_lshl_add_u64 v[34:35], s[40:41], 0, v[34:35]
	v_add_f32_e32 v30, 1.0, v30
	v_rcp_f32_e32 v22, v22
	v_add_f32_e32 v31, 1.0, v31
	v_rcp_f32_e32 v23, v23
	v_lshl_add_u64 v[34:35], v[34:35], 0, s[4:5]
	v_rcp_f32_e32 v30, v30
	v_rcp_f32_e32 v31, v31
	v_lshl_add_u64 v[34:35], v[34:35], 0, s[12:13]
	v_lshl_add_u64 v[46:47], v[34:35], 0, v[0:1]
	v_cvt_pk_bf16_f32 v34, v38, v39
	v_cvt_pk_bf16_f32 v35, v40, v41
	v_cvt_pk_bf16_f32 v36, v42, v43
	v_cvt_pk_bf16_f32 v37, v44, v45
	v_pk_mul_f32 v[24:25], v[24:25], v[186:187] op_sel_hi:[1,0]
	s_waitcnt vmcnt(3)
; __device__ __forceinline__ float sigmoidf_(float x) { return __builtin_amdgcn_rcpf(1.0f + __builtin_amdgcn_exp2f(-1.4426950408889634f * x)); }
; #define PG8_BAR __builtin_amdgcn_s_barrier()
;     __device__ __forceinline__ void operator()(const f32x4 (&acc)[2][2][4][2], const Unit& u, int wr, int wc, int fr, int fq) const {
;     ...
;                 if (mode == EP_GATE) {
;                     const size_t off = (size_t)row * DM + u.pn * 128 + wc * 32 + 8 * fq;
;                     const f32x4 a0 = acc[ai][0][m][0] * rs1, a1 = acc[ai][0][m][1] * rs1, b0 = acc[ai][1][m][0] * rs1, b1 = acc[ai][1][m][1] * rs1;
;                     const u32x4 y1 = yall[ai][m][0], y2 = yall[ai][m][1];
;                     f32x4 r0, r1;
;                     r0[0] = sigmoidf_(a0[0]) * bf_lo(y1.x) + sigmoidf_(b0[0]) * bf_lo(y2.x); r0[1] = sigmoidf_(a0[1]) * bf_hi(y1.x) + sigmoidf_(b0[1]) * bf_hi(y2.x);
;                     r0[2] = sigmoidf_(a0[2]) * bf_lo(y1.y) + sigmoidf_(b0[2]) * bf_lo(y2.y); r0[3] = sigmoidf_(a0[3]) * bf_hi(y1.y) + sigmoidf_(b0[3]) * bf_hi(y2.y);
;                     r1[0] = sigmoidf_(a1[0]) * bf_lo(y1.z) + sigmoidf_(b1[0]) * bf_lo(y2.z); r1[1] = sigmoidf_(a1[1]) * bf_hi(y1.z) + sigmoidf_(b1[1]) * bf_hi(y2.z);
;                     r1[2] = sigmoidf_(a1[2]) * bf_lo(y1.w) + sigmoidf_(b1[2]) * bf_lo(y2.w); r1[3] = sigmoidf_(a1[3]) * bf_hi(y1.w) + sigmoidf_(b1[3]) * bf_hi(y2.w);
;                     store8(O + off, r0, r1);
; template <class Epi, class Sched, bool ALIGN_EPI = false, bool SP2 = false>
; __device__ __forceinline__ void gemm_phase(PG8_LAS unsigned char* lds, const Gemm g, const Sched& S, const Epi& E, int wv) {
;     ...
;         if constexpr (ALIGN_EPI) { if (wr == 0) PG8_BAR; }
;         if constexpr (!Epi::AFTER_DRAIN) { E(acc, cur, wr, wc, fr, fq); S.done(cur); }
;         if (!has_next) break;
; #pragma unroll
;         for (int a = 0; a < 2; ++a)
; #pragma unroll
;             for (int b = 0; b < 2; ++b)
; #pragma unroll
;                 for (int m = 0; m < 4; ++m)
; #pragma unroll
;                     for (int n = 0; n < 2; ++n) acc[a][b][m][n] = (f32x4){0.f, 0.f, 0.f, 0.f};
;         cur = nxt; cA = nA; cB = nB; ++ui;
;         if constexpr (ALIGN_EPI) { if (wr == 1) PG8_BAR; }
	v_lshlrev_b32_e32 v38, 16, v78
	v_and_b32_e32 v39, 0xffff0000, v78
	global_store_dwordx4 v[46:47], v[34:37], off
	v_pk_mul_f32 v[32:33], v[32:33], v[186:187] op_sel_hi:[1,0]
	v_pk_mul_f32 v[22:23], v[22:23], v[38:39]
	v_lshlrev_b32_e32 v36, 16, v74
	v_and_b32_e32 v37, 0xffff0000, v74
	v_mul_f32_e32 v24, 0xbfb8aa3b, v24
	v_mul_f32_e32 v25, 0xbfb8aa3b, v25
	v_pk_mul_f32 v[18:19], v[18:19], v[186:187] op_sel_hi:[1,0]
	v_pk_fma_f32 v[22:23], v[30:31], v[36:37], v[22:23]
	v_mul_f32_e32 v30, 0xbfb8aa3b, v32
	v_exp_f32_e32 v24, v24
	v_mul_f32_e32 v31, 0xbfb8aa3b, v33
	v_exp_f32_e32 v25, v25
	v_pk_mul_f32 v[26:27], v[26:27], v[186:187] op_sel_hi:[1,0]
	v_exp_f32_e32 v30, v30
	v_exp_f32_e32 v31, v31
	v_mul_f32_e32 v18, 0xbfb8aa3b, v18
	v_mul_f32_e32 v19, 0xbfb8aa3b, v19
	v_mul_f32_e32 v26, 0xbfb8aa3b, v26
	v_exp_f32_e32 v18, v18
	v_mul_f32_e32 v27, 0xbfb8aa3b, v27
	v_exp_f32_e32 v19, v19
	v_exp_f32_e32 v26, v26
	v_exp_f32_e32 v27, v27
	v_add_f32_e32 v24, 1.0, v24
	v_add_f32_e32 v25, 1.0, v25
	v_add_f32_e32 v30, 1.0, v30
	v_rcp_f32_e32 v24, v24
	v_add_f32_e32 v31, 1.0, v31
	v_rcp_f32_e32 v25, v25
	v_rcp_f32_e32 v30, v30
	v_rcp_f32_e32 v31, v31
	v_add_f32_e32 v18, 1.0, v18
	v_add_f32_e32 v19, 1.0, v19
	v_add_f32_e32 v26, 1.0, v26
	v_rcp_f32_e32 v18, v18
	v_add_f32_e32 v27, 1.0, v27
	v_rcp_f32_e32 v19, v19
	v_lshlrev_b32_e32 v36, 16, v79
	v_and_b32_e32 v37, 0xffff0000, v79
	v_rcp_f32_e32 v26, v26
	v_rcp_f32_e32 v27, v27
	v_lshlrev_b32_e32 v32, 16, v75
	v_and_b32_e32 v33, 0xffff0000, v75
	v_pk_mul_f32 v[24:25], v[24:25], v[36:37]
	v_pk_mul_f32 v[20:21], v[20:21], v[186:187] op_sel_hi:[1,0]
	v_pk_fma_f32 v[24:25], v[30:31], v[32:33], v[24:25]
	v_lshlrev_b32_e32 v32, 16, v80
	v_and_b32_e32 v33, 0xffff0000, v80
	v_lshlrev_b32_e32 v30, 16, v76
	v_and_b32_e32 v31, 0xffff0000, v76
	v_pk_mul_f32 v[18:19], v[18:19], v[32:33]
	v_pk_mul_f32 v[28:29], v[28:29], v[186:187] op_sel_hi:[1,0]
	v_pk_fma_f32 v[26:27], v[26:27], v[30:31], v[18:19]
	v_mul_f32_e32 v19, 0xbfb8aa3b, v20
	v_exp_f32_e32 v19, v19
	v_mul_f32_e32 v21, 0xbfb8aa3b, v21
	v_mul_f32_e32 v18, 0xbfb8aa3b, v28
	v_exp_f32_e32 v21, v21
	v_add_f32_e32 v19, 1.0, v19
	v_rcp_f32_e32 v20, v19
	v_mul_f32_e32 v19, 0xbfb8aa3b, v29
	v_exp_f32_e32 v18, v18
	v_exp_f32_e32 v19, v19
	v_add_f32_e32 v21, 1.0, v21
	v_pk_mul_f32 v[6:7], v[6:7], v[180:181] op_sel_hi:[1,0]
	v_add_f32_e32 v18, 1.0, v18
	v_add_f32_e32 v19, 1.0, v19
	v_rcp_f32_e32 v21, v21
	v_pk_mul_f32 v[14:15], v[14:15], v[180:181] op_sel_hi:[1,0]
	v_mul_f32_e32 v6, 0xbfb8aa3b, v6
	v_mul_f32_e32 v7, 0xbfb8aa3b, v7
	v_rcp_f32_e32 v18, v18
	v_rcp_f32_e32 v19, v19
	v_mul_f32_e32 v14, 0xbfb8aa3b, v14
	v_exp_f32_e32 v6, v6
	v_mul_f32_e32 v15, 0xbfb8aa3b, v15
	v_exp_f32_e32 v7, v7
	v_exp_f32_e32 v14, v14
	v_exp_f32_e32 v15, v15
	v_lshlrev_b32_e32 v30, 16, v81
	v_and_b32_e32 v31, 0xffff0000, v81
	v_lshlrev_b64 v[34:35], 11, v[182:183]
	v_lshlrev_b32_e32 v28, 16, v77
	v_and_b32_e32 v29, 0xffff0000, v77
	v_pk_mul_f32 v[20:21], v[20:21], v[30:31]
	v_add_f32_e32 v6, 1.0, v6
	v_pk_fma_f32 v[28:29], v[18:19], v[28:29], v[20:21]
	v_lshl_add_u64 v[18:19], s[40:41], 0, v[34:35]
	v_add_f32_e32 v7, 1.0, v7
	v_lshl_add_u64 v[18:19], v[18:19], 0, s[4:5]
	v_add_f32_e32 v14, 1.0, v14
	v_rcp_f32_e32 v6, v6
	v_add_f32_e32 v15, 1.0, v15
	v_rcp_f32_e32 v7, v7
	v_lshl_add_u64 v[18:19], v[18:19], 0, s[12:13]
	v_rcp_f32_e32 v14, v14
	v_rcp_f32_e32 v15, v15
	v_lshl_add_u64 v[30:31], v[18:19], 0, v[0:1]
	v_cvt_pk_bf16_f32 v18, v22, v23
	v_cvt_pk_bf16_f32 v19, v24, v25
	v_cvt_pk_bf16_f32 v20, v26, v27
	v_cvt_pk_bf16_f32 v21, v28, v29
	global_store_dwordx4 v[30:31], v[18:21], off
	v_pk_mul_f32 v[8:9], v[8:9], v[180:181] op_sel_hi:[1,0]
	v_pk_mul_f32 v[16:17], v[16:17], v[180:181] op_sel_hi:[1,0]
	s_waitcnt vmcnt(3)
	v_lshlrev_b32_e32 v20, 16, v70
	v_and_b32_e32 v21, 0xffff0000, v70
	v_lshlrev_b32_e32 v18, 16, v66
	v_and_b32_e32 v19, 0xffff0000, v66
	v_pk_mul_f32 v[6:7], v[6:7], v[20:21]
	v_mul_f32_e32 v8, 0xbfb8aa3b, v8
	v_mul_f32_e32 v9, 0xbfb8aa3b, v9
	v_pk_mul_f32 v[2:3], v[2:3], v[180:181] op_sel_hi:[1,0]
	v_pk_fma_f32 v[6:7], v[14:15], v[18:19], v[6:7]
	v_mul_f32_e32 v14, 0xbfb8aa3b, v16
	v_exp_f32_e32 v8, v8
	v_mul_f32_e32 v15, 0xbfb8aa3b, v17
	v_exp_f32_e32 v9, v9
	v_pk_mul_f32 v[10:11], v[10:11], v[180:181] op_sel_hi:[1,0]
	v_exp_f32_e32 v14, v14
	v_exp_f32_e32 v15, v15
	v_mul_f32_e32 v2, 0xbfb8aa3b, v2
	v_mul_f32_e32 v3, 0xbfb8aa3b, v3
	v_mul_f32_e32 v10, 0xbfb8aa3b, v10
	v_exp_f32_e32 v2, v2
	v_mul_f32_e32 v11, 0xbfb8aa3b, v11
	v_exp_f32_e32 v3, v3
	v_exp_f32_e32 v10, v10
	v_exp_f32_e32 v11, v11
	v_add_f32_e32 v8, 1.0, v8
	v_add_f32_e32 v9, 1.0, v9
	v_add_f32_e32 v14, 1.0, v14
	v_rcp_f32_e32 v8, v8
	v_add_f32_e32 v15, 1.0, v15
	v_rcp_f32_e32 v9, v9
	v_rcp_f32_e32 v14, v14
	v_rcp_f32_e32 v15, v15
	v_add_f32_e32 v2, 1.0, v2
	v_add_f32_e32 v3, 1.0, v3
	v_add_f32_e32 v10, 1.0, v10
	v_rcp_f32_e32 v2, v2
	v_add_f32_e32 v11, 1.0, v11
	v_rcp_f32_e32 v3, v3
	v_lshlrev_b32_e32 v18, 16, v71
	v_and_b32_e32 v19, 0xffff0000, v71
	v_rcp_f32_e32 v10, v10
	v_rcp_f32_e32 v11, v11
	v_lshlrev_b32_e32 v16, 16, v67
	v_and_b32_e32 v17, 0xffff0000, v67
	v_pk_mul_f32 v[8:9], v[8:9], v[18:19]
	v_pk_mul_f32 v[4:5], v[4:5], v[180:181] op_sel_hi:[1,0]
	v_pk_fma_f32 v[8:9], v[14:15], v[16:17], v[8:9]
	v_lshlrev_b32_e32 v16, 16, v72
	v_and_b32_e32 v17, 0xffff0000, v72
	v_lshlrev_b32_e32 v14, 16, v68
	v_and_b32_e32 v15, 0xffff0000, v68
	v_pk_mul_f32 v[2:3], v[2:3], v[16:17]
	v_pk_mul_f32 v[12:13], v[12:13], v[180:181] op_sel_hi:[1,0]
	v_pk_fma_f32 v[10:11], v[10:11], v[14:15], v[2:3]
	v_mul_f32_e32 v3, 0xbfb8aa3b, v4
	v_exp_f32_e32 v3, v3
	v_mul_f32_e32 v5, 0xbfb8aa3b, v5
	v_mul_f32_e32 v2, 0xbfb8aa3b, v12
	v_exp_f32_e32 v5, v5
	v_add_f32_e32 v3, 1.0, v3
	v_rcp_f32_e32 v4, v3
	v_mul_f32_e32 v3, 0xbfb8aa3b, v13
	v_exp_f32_e32 v2, v2
	v_exp_f32_e32 v3, v3
	v_add_f32_e32 v5, 1.0, v5
	v_rcp_f32_e32 v5, v5
	v_add_f32_e32 v2, 1.0, v2
	v_add_f32_e32 v3, 1.0, v3
	v_rcp_f32_e32 v2, v2
	v_rcp_f32_e32 v3, v3
	v_lshlrev_b32_e32 v14, 16, v73
	v_and_b32_e32 v15, 0xffff0000, v73
	v_lshlrev_b32_e32 v12, 16, v69
	v_and_b32_e32 v13, 0xffff0000, v69
	v_pk_mul_f32 v[4:5], v[4:5], v[14:15]
	v_mov_b32_e32 v195, 0x3727c5ac
	v_pk_fma_f32 v[12:13], v[2:3], v[12:13], v[4:5]
	v_lshlrev_b64 v[2:3], 11, v[178:179]
	v_lshl_add_u64 v[2:3], s[40:41], 0, v[2:3]
	v_lshl_add_u64 v[2:3], v[2:3], 0, s[4:5]
	v_lshl_add_u64 v[2:3], v[2:3], 0, s[12:13]
	v_lshl_add_u64 v[14:15], v[2:3], 0, v[0:1]
	v_cvt_pk_bf16_f32 v2, v6, v7
	v_cvt_pk_bf16_f32 v3, v8, v9
	v_cvt_pk_bf16_f32 v4, v10, v11
	v_cvt_pk_bf16_f32 v5, v12, v13
	s_mov_b64 s[4:5], -1
	global_store_dwordx4 v[14:15], v[2:5], off
	s_cbranch_vccnz .LBB0_1075
	s_andn2_b64 vcc, exec, s[0:1]
	s_cbranch_vccnz .LBB0_1074
	s_barrier
	s_branch .LBB0_1074

;     __device__ __forceinline__ void operator()(const f32x4 (&acc)[2][2][4][2], const Unit& u, int wr, int wc, int fr, int fq) const {
;     ...
;                         const size_t off = (size_t)row * DM + col8;
;                         const u32x4 xi = yall[ai][m][bj];
;                         const f32x4 x0 = (f32x4){bf_lo(xi.x), bf_hi(xi.x), bf_lo(xi.y), bf_hi(xi.y)} + v0, x1 = (f32x4){bf_lo(xi.z), bf_hi(xi.z), bf_lo(xi.w), bf_hi(xi.w)} + v1;
;                         store8(xb + off, x0, x1);
;                         ssacc += (x0[0] * x0[0] + x0[1] * x0[1]) + (x0[2] * x0[2] + x0[3] * x0[3]) + (x1[0] * x1[0] + x1[1] * x1[1]) + (x1[2] * x1[2] + x1[3] * x1[3]);
;                     }
;                 }
;                 if (mode == EP_RESID) {
;                     ssacc += __shfl_xor(ssacc, 16); ssacc += __shfl_xor(ssacc, 32);
;                     if (fq == 0) ss_out[(size_t)row * 16 + u.pn * 4 + wc] = ssacc;
;                 }
.LBB0_1150:
	v_lshl_add_u32 v174, s12, 8, v188
	s_lshl_b32 s28, s54, 8
	s_ashr_i32 s29, s28, 31
	v_ashrrev_i32_e32 v175, 31, v174
	v_lshl_add_u64 v[172:173], s[28:29], 1, v[164:165]
	v_lshlrev_b64 v[192:193], 11, v[174:175]
	v_lshl_add_u64 v[130:131], v[172:173], 0, v[192:193]
	global_load_dwordx4 v[196:199], v[130:131], off
	global_load_dwordx4 v[154:157], v[130:131], off offset:256
	v_or_b32_e32 v184, 16, v174
	v_ashrrev_i32_e32 v185, 31, v184
	v_or_b32_e32 v178, 32, v174
	v_lshlrev_b64 v[186:187], 11, v[184:185]
	v_ashrrev_i32_e32 v179, 31, v178
	v_or_b32_e32 v176, 48, v174
	v_lshl_add_u64 v[130:131], v[172:173], 0, v[186:187]
	v_lshlrev_b64 v[182:183], 11, v[178:179]
	v_ashrrev_i32_e32 v177, 31, v176
	global_load_dwordx4 v[150:153], v[130:131], off
	global_load_dwordx4 v[146:149], v[130:131], off offset:256
	v_lshl_add_u64 v[130:131], v[172:173], 0, v[182:183]
	v_lshlrev_b64 v[180:181], 11, v[176:177]
	global_load_dwordx4 v[142:145], v[130:131], off
	global_load_dwordx4 v[138:141], v[130:131], off offset:256
	v_lshl_add_u64 v[130:131], v[172:173], 0, v[180:181]
	global_load_dwordx4 v[134:137], v[130:131], off
	s_nop 0
	global_load_dwordx4 v[130:133], v[130:131], off offset:256
	v_or_b32_e32 v170, s28, v190
	v_ashrrev_i32_e32 v171, 31, v170
	s_waitcnt vmcnt(0)
	v_lshlrev_b32_e32 v200, 16, v196
	v_and_b32_e32 v201, 0xffff0000, v196
	v_lshlrev_b32_e32 v196, 16, v197
	v_and_b32_e32 v197, 0xffff0000, v197
	v_pk_add_f32 v[128:129], v[128:129], v[196:197]
	v_lshlrev_b32_e32 v196, 16, v198
	v_and_b32_e32 v197, 0xffff0000, v198
	v_lshlrev_b32_e32 v198, 16, v199
	v_and_b32_e32 v199, 0xffff0000, v199
	v_pk_add_f32 v[126:127], v[126:127], v[200:201]
	v_pk_add_f32 v[198:199], v[124:125], v[198:199]
	v_pk_add_f32 v[196:197], v[122:123], v[196:197]
	v_lshl_add_u64 v[122:123], s[6:7], 0, v[192:193]
	v_lshl_add_u64 v[192:193], v[170:171], 1, v[122:123]
	v_cvt_pk_bf16_f32 v122, v126, v127
	v_cvt_pk_bf16_f32 v123, v128, v129
	v_cvt_pk_bf16_f32 v124, v196, v197
	v_cvt_pk_bf16_f32 v125, v198, v199
	global_store_dwordx4 v[192:193], v[122:125], off
	s_nop 1
	v_mul_f32_e32 v122, v127, v127
	v_mul_f32_e32 v123, v129, v129
	v_fmac_f32_e32 v122, v126, v126
	v_fmac_f32_e32 v123, v128, v128
	v_add_f32_e32 v122, v122, v123
	v_mul_f32_e32 v123, v197, v197
	v_fmac_f32_e32 v123, v196, v196
	v_add_f32_e32 v122, v123, v122
	v_mul_f32_e32 v123, v199, v199
	v_fmac_f32_e32 v123, v198, v198
	v_add_f32_e32 v126, v123, v122
	v_lshlrev_b32_e32 v122, 16, v154
	v_and_b32_e32 v123, 0xffff0000, v154
	v_lshlrev_b32_e32 v124, 16, v155
	v_and_b32_e32 v125, 0xffff0000, v155
	v_pk_add_f32 v[120:121], v[120:121], v[124:125]
	v_pk_add_f32 v[118:119], v[118:119], v[122:123]
	v_lshlrev_b32_e32 v122, 16, v156
	v_and_b32_e32 v123, 0xffff0000, v156
	v_lshlrev_b32_e32 v124, 16, v157
	v_and_b32_e32 v125, 0xffff0000, v157
	v_pk_add_f32 v[124:125], v[116:117], v[124:125]
	v_pk_add_f32 v[122:123], v[114:115], v[122:123]
	v_cvt_pk_bf16_f32 v114, v118, v119
	v_cvt_pk_bf16_f32 v115, v120, v121
	v_cvt_pk_bf16_f32 v116, v122, v123
	v_cvt_pk_bf16_f32 v117, v124, v125
	global_store_dwordx4 v[192:193], v[114:117], off offset:256
	s_nop 1
	v_mul_f32_e32 v114, v119, v119
	v_mul_f32_e32 v115, v121, v121
	v_fmac_f32_e32 v114, v118, v118
	v_fmac_f32_e32 v115, v120, v120
	v_add_f32_e32 v114, v114, v115
	v_mul_f32_e32 v115, v123, v123
	v_fmac_f32_e32 v115, v122, v122
	v_add_f32_e32 v114, v115, v114
	v_mul_f32_e32 v115, v125, v125
	v_fmac_f32_e32 v115, v124, v124
	v_add_f32_e32 v114, v115, v114
	v_add_f32_e32 v114, v126, v114
	v_mov_b32_e32 v115, v114
	s_nop 1
	v_permlane16_swap_b32 v114, v115
	s_nop 1
	s_waitcnt lgkmcnt(0)
	v_add_f32_e32 v114, v114, v115
	v_mov_b32_e32 v115, v114
	s_nop 1
	v_permlane32_swap_b32 v114, v115
	s_nop 1
	s_and_saveexec_b64 s[16:17], s[0:1]
	s_cbranch_execz .LBB0_1152
	s_waitcnt lgkmcnt(0)
	v_add_f32_e32 v116, v114, v115
	s_lshl_b32 s28, s54, 2
	v_lshlrev_b64 v[114:115], 6, v[174:175]
	s_ashr_i32 s29, s28, 31
	v_lshl_add_u64 v[114:115], s[8:9], 0, v[114:115]
	v_lshl_add_u64 v[114:115], s[28:29], 2, v[114:115]
	s_lshl_b32 s12, s50, 2
	v_lshl_add_u64 v[114:115], v[114:115], 0, s[12:13]
	global_store_dword v[114:115], v116, off
.LBB0_1152:
	s_or_b64 exec, exec, s[16:17]
	v_lshlrev_b32_e32 v114, 16, v150
	s_waitcnt lgkmcnt(0)
	v_and_b32_e32 v115, 0xffff0000, v150
	v_lshlrev_b32_e32 v116, 16, v151
	v_and_b32_e32 v117, 0xffff0000, v151
	v_pk_add_f32 v[112:113], v[112:113], v[116:117]
	v_pk_add_f32 v[110:111], v[110:111], v[114:115]
	v_lshlrev_b32_e32 v114, 16, v152
	v_and_b32_e32 v115, 0xffff0000, v152
	v_lshlrev_b32_e32 v116, 16, v153
	v_and_b32_e32 v117, 0xffff0000, v153
	v_pk_add_f32 v[116:117], v[108:109], v[116:117]
	v_pk_add_f32 v[108:109], v[106:107], v[114:115]
	v_lshl_add_u64 v[106:107], s[6:7], 0, v[186:187]
	v_lshl_add_u64 v[114:115], v[170:171], 1, v[106:107]
	v_cvt_pk_bf16_f32 v106, v110, v111
	v_mul_f32_e32 v111, v111, v111
	v_fmac_f32_e32 v111, v110, v110
	v_mul_f32_e32 v110, v113, v113
	v_fmac_f32_e32 v110, v112, v112
	v_add_f32_e32 v110, v111, v110
	v_mul_f32_e32 v111, v109, v109
	v_fmac_f32_e32 v111, v108, v108
	v_add_f32_e32 v110, v111, v110
	v_mul_f32_e32 v111, v117, v117
	v_fmac_f32_e32 v111, v116, v116
	v_cvt_pk_bf16_f32 v107, v112, v113
	v_add_f32_e32 v118, v111, v110
	v_lshlrev_b32_e32 v110, 16, v146
	v_and_b32_e32 v111, 0xffff0000, v146
	v_lshlrev_b32_e32 v112, 16, v147
	v_and_b32_e32 v113, 0xffff0000, v147
	v_pk_add_f32 v[104:105], v[104:105], v[112:113]
	v_pk_add_f32 v[102:103], v[102:103], v[110:111]
	v_lshlrev_b32_e32 v110, 16, v148
	v_and_b32_e32 v111, 0xffff0000, v148
	v_pk_add_f32 v[110:111], v[98:99], v[110:111]
	v_mul_f32_e32 v98, v103, v103
	v_mul_f32_e32 v99, v105, v105
	v_fmac_f32_e32 v98, v102, v102
	v_fmac_f32_e32 v99, v104, v104
	v_lshlrev_b32_e32 v112, 16, v149
	v_and_b32_e32 v113, 0xffff0000, v149
	v_add_f32_e32 v98, v98, v99
	v_mul_f32_e32 v99, v111, v111
	v_pk_add_f32 v[112:113], v[100:101], v[112:113]
	v_fmac_f32_e32 v99, v110, v110
	v_add_f32_e32 v98, v99, v98
	v_mul_f32_e32 v99, v113, v113
	v_fmac_f32_e32 v99, v112, v112
	v_add_f32_e32 v98, v99, v98
	v_add_f32_e32 v98, v118, v98
	v_mov_b32_e32 v99, v98
	s_nop 1
	v_permlane16_swap_b32 v98, v99
	s_nop 1
	v_cvt_pk_bf16_f32 v108, v108, v109
	v_cvt_pk_bf16_f32 v109, v116, v117
	v_cvt_pk_bf16_f32 v100, v102, v103
	v_cvt_pk_bf16_f32 v101, v104, v105
	s_waitcnt lgkmcnt(0)
	v_add_f32_e32 v98, v98, v99
	v_mov_b32_e32 v99, v98
	s_nop 1
	v_permlane32_swap_b32 v98, v99
	s_nop 1
	v_cvt_pk_bf16_f32 v102, v110, v111
	v_cvt_pk_bf16_f32 v103, v112, v113
	global_store_dwordx4 v[114:115], v[106:109], off
	global_store_dwordx4 v[114:115], v[100:103], off offset:256
	s_and_saveexec_b64 s[16:17], s[0:1]
	s_cbranch_execz .LBB0_1154
	s_waitcnt lgkmcnt(0)
	v_add_f32_e32 v100, v98, v99
	s_lshl_b32 s28, s54, 2
	v_lshlrev_b64 v[98:99], 6, v[184:185]
	s_ashr_i32 s29, s28, 31
	v_lshl_add_u64 v[98:99], s[8:9], 0, v[98:99]
	v_lshl_add_u64 v[98:99], s[28:29], 2, v[98:99]
	s_lshl_b32 s12, s50, 2
	v_lshl_add_u64 v[98:99], v[98:99], 0, s[12:13]
	global_store_dword v[98:99], v100, off
;     __device__ __forceinline__ void operator()(const f32x4 (&acc)[2][2][4][2], const Unit& u, int wr, int wc, int fr, int fq) const {
;     ...
;                         const size_t off = (size_t)row * DM + col8;
;                         const u32x4 xi = yall[ai][m][bj];
;                         const f32x4 x0 = (f32x4){bf_lo(xi.x), bf_hi(xi.x), bf_lo(xi.y), bf_hi(xi.y)} + v0, x1 = (f32x4){bf_lo(xi.z), bf_hi(xi.z), bf_lo(xi.w), bf_hi(xi.w)} + v1;
;                         store8(xb + off, x0, x1);
;                         ssacc += (x0[0] * x0[0] + x0[1] * x0[1]) + (x0[2] * x0[2] + x0[3] * x0[3]) + (x1[0] * x1[0] + x1[1] * x1[1]) + (x1[2] * x1[2] + x1[3] * x1[3]);
;                     }
;                 }
;                 if (mode == EP_RESID) {
;                     ssacc += __shfl_xor(ssacc, 16); ssacc += __shfl_xor(ssacc, 32);
;                     if (fq == 0) ss_out[(size_t)row * 16 + u.pn * 4 + wc] = ssacc;
;                 }
.LBB0_1154:
	s_or_b64 exec, exec, s[16:17]
	v_lshlrev_b32_e32 v98, 16, v142
	s_waitcnt lgkmcnt(0)
	v_and_b32_e32 v99, 0xffff0000, v142
	v_lshlrev_b32_e32 v100, 16, v143
	v_and_b32_e32 v101, 0xffff0000, v143
	v_pk_add_f32 v[96:97], v[96:97], v[100:101]
	v_pk_add_f32 v[94:95], v[94:95], v[98:99]
	v_lshlrev_b32_e32 v98, 16, v144
	v_and_b32_e32 v99, 0xffff0000, v144
	v_lshlrev_b32_e32 v100, 16, v145
	v_and_b32_e32 v101, 0xffff0000, v145
	v_pk_add_f32 v[100:101], v[92:93], v[100:101]
	v_pk_add_f32 v[92:93], v[90:91], v[98:99]
	v_lshl_add_u64 v[90:91], s[6:7], 0, v[182:183]
	v_lshl_add_u64 v[98:99], v[170:171], 1, v[90:91]
	v_cvt_pk_bf16_f32 v90, v94, v95
	v_mul_f32_e32 v95, v95, v95
	v_fmac_f32_e32 v95, v94, v94
	v_mul_f32_e32 v94, v97, v97
	v_fmac_f32_e32 v94, v96, v96
	v_add_f32_e32 v94, v95, v94
	v_mul_f32_e32 v95, v93, v93
	v_fmac_f32_e32 v95, v92, v92
	v_add_f32_e32 v94, v95, v94
	v_mul_f32_e32 v95, v101, v101
	v_fmac_f32_e32 v95, v100, v100
	v_cvt_pk_bf16_f32 v91, v96, v97
	v_add_f32_e32 v102, v95, v94
	v_lshlrev_b32_e32 v94, 16, v138
	v_and_b32_e32 v95, 0xffff0000, v138
	v_lshlrev_b32_e32 v96, 16, v139
	v_and_b32_e32 v97, 0xffff0000, v139
	v_pk_add_f32 v[88:89], v[88:89], v[96:97]
	v_pk_add_f32 v[86:87], v[86:87], v[94:95]
	v_lshlrev_b32_e32 v94, 16, v140
	v_and_b32_e32 v95, 0xffff0000, v140
	v_pk_add_f32 v[94:95], v[82:83], v[94:95]
	v_mul_f32_e32 v82, v87, v87
	v_mul_f32_e32 v83, v89, v89
	v_fmac_f32_e32 v82, v86, v86
	v_fmac_f32_e32 v83, v88, v88
	v_lshlrev_b32_e32 v96, 16, v141
	v_and_b32_e32 v97, 0xffff0000, v141
	v_add_f32_e32 v82, v82, v83
	v_mul_f32_e32 v83, v95, v95
	v_pk_add_f32 v[96:97], v[84:85], v[96:97]
	v_fmac_f32_e32 v83, v94, v94
	v_add_f32_e32 v82, v83, v82
	v_mul_f32_e32 v83, v97, v97
	v_fmac_f32_e32 v83, v96, v96
	v_add_f32_e32 v82, v83, v82
	v_add_f32_e32 v82, v102, v82
	v_mov_b32_e32 v83, v82
	s_nop 1
	v_permlane16_swap_b32 v82, v83
	s_nop 1
	v_cvt_pk_bf16_f32 v92, v92, v93
	v_cvt_pk_bf16_f32 v93, v100, v101
	v_cvt_pk_bf16_f32 v84, v86, v87
	v_cvt_pk_bf16_f32 v85, v88, v89
	s_waitcnt lgkmcnt(0)
	v_add_f32_e32 v82, v82, v83
	v_mov_b32_e32 v83, v82
	s_nop 1
	v_permlane32_swap_b32 v82, v83
	s_nop 1
	v_cvt_pk_bf16_f32 v86, v94, v95
	v_cvt_pk_bf16_f32 v87, v96, v97
	global_store_dwordx4 v[98:99], v[90:93], off
	global_store_dwordx4 v[98:99], v[84:87], off offset:256
	s_and_saveexec_b64 s[16:17], s[0:1]
	s_cbranch_execz .LBB0_1156
	s_waitcnt lgkmcnt(0)
	v_add_f32_e32 v84, v82, v83
	s_lshl_b32 s28, s54, 2
	v_lshlrev_b64 v[82:83], 6, v[178:179]
	s_ashr_i32 s29, s28, 31
	v_lshl_add_u64 v[82:83], s[8:9], 0, v[82:83]
	v_lshl_add_u64 v[82:83], s[28:29], 2, v[82:83]
	s_lshl_b32 s12, s50, 2
	v_lshl_add_u64 v[82:83], v[82:83], 0, s[12:13]
	global_store_dword v[82:83], v84, off
.LBB0_1156:
	s_or_b64 exec, exec, s[16:17]
	v_lshlrev_b32_e32 v82, 16, v134
	s_waitcnt lgkmcnt(0)
	v_and_b32_e32 v83, 0xffff0000, v134
	v_lshlrev_b32_e32 v84, 16, v135
	v_and_b32_e32 v85, 0xffff0000, v135
	v_pk_add_f32 v[80:81], v[80:81], v[84:85]
	v_pk_add_f32 v[78:79], v[78:79], v[82:83]
	v_lshlrev_b32_e32 v82, 16, v136
	v_and_b32_e32 v83, 0xffff0000, v136
	v_lshlrev_b32_e32 v84, 16, v137
	v_and_b32_e32 v85, 0xffff0000, v137
	v_pk_add_f32 v[84:85], v[76:77], v[84:85]
	v_pk_add_f32 v[76:77], v[74:75], v[82:83]
	v_lshl_add_u64 v[74:75], s[6:7], 0, v[180:181]
	v_lshl_add_u64 v[82:83], v[170:171], 1, v[74:75]
	v_cvt_pk_bf16_f32 v74, v78, v79
	v_mul_f32_e32 v79, v79, v79
	v_fmac_f32_e32 v79, v78, v78
	v_mul_f32_e32 v78, v81, v81
	v_fmac_f32_e32 v78, v80, v80
	v_add_f32_e32 v78, v79, v78
	v_mul_f32_e32 v79, v77, v77
	v_fmac_f32_e32 v79, v76, v76
	v_add_f32_e32 v78, v79, v78
	v_mul_f32_e32 v79, v85, v85
	v_fmac_f32_e32 v79, v84, v84
	v_cvt_pk_bf16_f32 v75, v80, v81
	v_add_f32_e32 v86, v79, v78
	v_lshlrev_b32_e32 v78, 16, v130
	v_and_b32_e32 v79, 0xffff0000, v130
	v_lshlrev_b32_e32 v80, 16, v131
	v_and_b32_e32 v81, 0xffff0000, v131
	v_pk_add_f32 v[72:73], v[72:73], v[80:81]
	v_pk_add_f32 v[70:71], v[70:71], v[78:79]
	v_lshlrev_b32_e32 v78, 16, v132
	v_and_b32_e32 v79, 0xffff0000, v132
	v_pk_add_f32 v[78:79], v[66:67], v[78:79]
	v_mul_f32_e32 v66, v71, v71
	v_mul_f32_e32 v67, v73, v73
	v_fmac_f32_e32 v66, v70, v70
	v_fmac_f32_e32 v67, v72, v72
	v_lshlrev_b32_e32 v80, 16, v133
	v_and_b32_e32 v81, 0xffff0000, v133
	v_add_f32_e32 v66, v66, v67
	v_mul_f32_e32 v67, v79, v79
	v_pk_add_f32 v[80:81], v[68:69], v[80:81]
	v_fmac_f32_e32 v67, v78, v78
	v_add_f32_e32 v66, v67, v66
	v_mul_f32_e32 v67, v81, v81
	v_fmac_f32_e32 v67, v80, v80
	v_add_f32_e32 v66, v67, v66
	v_add_f32_e32 v66, v86, v66
	v_mov_b32_e32 v67, v66
	s_nop 1
	v_permlane16_swap_b32 v66, v67
	s_nop 1
	v_cvt_pk_bf16_f32 v76, v76, v77
	v_cvt_pk_bf16_f32 v77, v84, v85
	v_cvt_pk_bf16_f32 v68, v70, v71
	v_cvt_pk_bf16_f32 v69, v72, v73
	s_waitcnt lgkmcnt(0)
	v_add_f32_e32 v66, v66, v67
	v_mov_b32_e32 v67, v66
	s_nop 1
	v_permlane32_swap_b32 v66, v67
	s_nop 1
	v_cvt_pk_bf16_f32 v70, v78, v79
	v_cvt_pk_bf16_f32 v71, v80, v81
	global_store_dwordx4 v[82:83], v[74:77], off
	global_store_dwordx4 v[82:83], v[68:71], off offset:256
	s_and_saveexec_b64 s[16:17], s[0:1]
	s_cbranch_execz .LBB0_1158
	s_waitcnt lgkmcnt(0)
	v_add_f32_e32 v68, v66, v67
	s_lshl_b32 s28, s54, 2
	v_lshlrev_b64 v[66:67], 6, v[176:177]
	s_ashr_i32 s29, s28, 31
	v_lshl_add_u64 v[66:67], s[8:9], 0, v[66:67]
	v_lshl_add_u64 v[66:67], s[28:29], 2, v[66:67]
	s_lshl_b32 s12, s50, 2
	v_lshl_add_u64 v[66:67], v[66:67], 0, s[12:13]
	global_store_dword v[66:67], v68, off
;     __device__ __forceinline__ void operator()(const f32x4 (&acc)[2][2][4][2], const Unit& u, int wr, int wc, int fr, int fq) const {
;     ...
;                         const size_t off = (size_t)row * DM + col8;
;                         const u32x4 xi = yall[ai][m][bj];
;                         const f32x4 x0 = (f32x4){bf_lo(xi.x), bf_hi(xi.x), bf_lo(xi.y), bf_hi(xi.y)} + v0, x1 = (f32x4){bf_lo(xi.z), bf_hi(xi.z), bf_lo(xi.w), bf_hi(xi.w)} + v1;
;                         store8(xb + off, x0, x1);
;                         ssacc += (x0[0] * x0[0] + x0[1] * x0[1]) + (x0[2] * x0[2] + x0[3] * x0[3]) + (x1[0] * x1[0] + x1[1] * x1[1]) + (x1[2] * x1[2] + x1[3] * x1[3]);
;                     }
;                 }
;                 if (mode == EP_RESID) {
;                     ssacc += __shfl_xor(ssacc, 16); ssacc += __shfl_xor(ssacc, 32);
;                     if (fq == 0) ss_out[(size_t)row * 16 + u.pn * 4 + wc] = ssacc;
;                 }
.LBB0_1158:
	s_or_b64 exec, exec, s[16:17]
	v_add_u32_e32 v106, 0x80, v174
	v_ashrrev_i32_e32 v107, 31, v106
	v_lshlrev_b64 v[112:113], 11, v[106:107]
	s_waitcnt lgkmcnt(0)
	v_lshl_add_u64 v[66:67], v[172:173], 0, v[112:113]
	global_load_dwordx4 v[108:111], v[66:67], off
	global_load_dwordx4 v[90:93], v[66:67], off offset:256
	v_add_u32_e32 v102, 0x90, v174
	v_ashrrev_i32_e32 v103, 31, v102
	v_add_u32_e32 v96, 0xa0, v174
	v_lshlrev_b64 v[104:105], 11, v[102:103]
	v_ashrrev_i32_e32 v97, 31, v96
	v_add_u32_e32 v94, 0xb0, v174
	v_lshl_add_u64 v[66:67], v[172:173], 0, v[104:105]
	v_lshlrev_b64 v[100:101], 11, v[96:97]
	v_ashrrev_i32_e32 v95, 31, v94
	global_load_dwordx4 v[86:89], v[66:67], off
	global_load_dwordx4 v[82:85], v[66:67], off offset:256
	v_lshl_add_u64 v[66:67], v[172:173], 0, v[100:101]
	v_lshlrev_b64 v[98:99], 11, v[94:95]
	global_load_dwordx4 v[78:81], v[66:67], off
	global_load_dwordx4 v[74:77], v[66:67], off offset:256
	v_lshl_add_u64 v[66:67], v[172:173], 0, v[98:99]
	global_load_dwordx4 v[70:73], v[66:67], off
	s_nop 0
	global_load_dwordx4 v[66:69], v[66:67], off offset:256
	s_waitcnt vmcnt(7)
	v_lshlrev_b32_e32 v114, 16, v108
	v_and_b32_e32 v115, 0xffff0000, v108
	v_lshlrev_b32_e32 v108, 16, v109
	v_and_b32_e32 v109, 0xffff0000, v109
	v_pk_add_f32 v[64:65], v[64:65], v[108:109]
	v_lshlrev_b32_e32 v108, 16, v110
	v_and_b32_e32 v109, 0xffff0000, v110
	v_lshlrev_b32_e32 v110, 16, v111
	v_and_b32_e32 v111, 0xffff0000, v111
	v_pk_add_f32 v[62:63], v[62:63], v[114:115]
	v_pk_add_f32 v[110:111], v[60:61], v[110:111]
	v_pk_add_f32 v[108:109], v[58:59], v[108:109]
	v_lshl_add_u64 v[58:59], s[6:7], 0, v[112:113]
	v_lshl_add_u64 v[112:113], v[170:171], 1, v[58:59]
	v_cvt_pk_bf16_f32 v58, v62, v63
	v_cvt_pk_bf16_f32 v59, v64, v65
	v_cvt_pk_bf16_f32 v60, v108, v109
	v_cvt_pk_bf16_f32 v61, v110, v111
	global_store_dwordx4 v[112:113], v[58:61], off
	s_nop 1
	v_mul_f32_e32 v58, v63, v63
	v_mul_f32_e32 v59, v65, v65
	v_fmac_f32_e32 v58, v62, v62
	v_fmac_f32_e32 v59, v64, v64
	v_add_f32_e32 v58, v58, v59
	v_mul_f32_e32 v59, v109, v109
	v_fmac_f32_e32 v59, v108, v108
	v_add_f32_e32 v58, v59, v58
	v_mul_f32_e32 v59, v111, v111
	v_fmac_f32_e32 v59, v110, v110
	v_add_f32_e32 v62, v59, v58
	s_waitcnt vmcnt(7)
	v_lshlrev_b32_e32 v58, 16, v90
	v_and_b32_e32 v59, 0xffff0000, v90
	v_lshlrev_b32_e32 v60, 16, v91
	v_and_b32_e32 v61, 0xffff0000, v91
	v_pk_add_f32 v[56:57], v[56:57], v[60:61]
	v_pk_add_f32 v[54:55], v[54:55], v[58:59]
	v_lshlrev_b32_e32 v58, 16, v92
	v_and_b32_e32 v59, 0xffff0000, v92
	v_lshlrev_b32_e32 v60, 16, v93
	v_and_b32_e32 v61, 0xffff0000, v93
	v_pk_add_f32 v[60:61], v[52:53], v[60:61]
	v_pk_add_f32 v[58:59], v[50:51], v[58:59]
	v_cvt_pk_bf16_f32 v50, v54, v55
	v_cvt_pk_bf16_f32 v51, v56, v57
	v_cvt_pk_bf16_f32 v52, v58, v59
	v_cvt_pk_bf16_f32 v53, v60, v61
	global_store_dwordx4 v[112:113], v[50:53], off offset:256
	s_nop 1
	v_mul_f32_e32 v50, v55, v55
	v_mul_f32_e32 v51, v57, v57
	v_fmac_f32_e32 v50, v54, v54
	v_fmac_f32_e32 v51, v56, v56
	v_add_f32_e32 v50, v50, v51
	v_mul_f32_e32 v51, v59, v59
	v_fmac_f32_e32 v51, v58, v58
	v_add_f32_e32 v50, v51, v50
	v_mul_f32_e32 v51, v61, v61
	v_fmac_f32_e32 v51, v60, v60
	v_add_f32_e32 v50, v51, v50
	v_add_f32_e32 v50, v62, v50
	v_mov_b32_e32 v51, v50
	s_nop 1
	v_permlane16_swap_b32 v50, v51
	s_nop 1
	s_waitcnt lgkmcnt(0)
	v_add_f32_e32 v50, v50, v51
	v_mov_b32_e32 v51, v50
	s_nop 1
	v_permlane32_swap_b32 v50, v51
	s_nop 1
	s_and_saveexec_b64 s[16:17], s[0:1]
	s_cbranch_execz .LBB0_1160
	s_waitcnt lgkmcnt(0)
	v_add_f32_e32 v52, v50, v51
	s_lshl_b32 s28, s54, 2
	v_lshlrev_b64 v[50:51], 6, v[106:107]
	s_ashr_i32 s29, s28, 31
	v_lshl_add_u64 v[50:51], s[8:9], 0, v[50:51]
	v_lshl_add_u64 v[50:51], s[28:29], 2, v[50:51]
	s_lshl_b32 s12, s50, 2
	v_lshl_add_u64 v[50:51], v[50:51], 0, s[12:13]
	global_store_dword v[50:51], v52, off
.LBB0_1160:
	s_or_b64 exec, exec, s[16:17]
	s_waitcnt vmcnt(7)
	v_lshlrev_b32_e32 v50, 16, v86
	s_waitcnt lgkmcnt(0)
	v_and_b32_e32 v51, 0xffff0000, v86
	v_lshlrev_b32_e32 v52, 16, v87
	v_and_b32_e32 v53, 0xffff0000, v87
	v_pk_add_f32 v[48:49], v[48:49], v[52:53]
	v_pk_add_f32 v[46:47], v[46:47], v[50:51]
	v_lshlrev_b32_e32 v50, 16, v88
	v_and_b32_e32 v51, 0xffff0000, v88
	v_lshlrev_b32_e32 v52, 16, v89
	v_and_b32_e32 v53, 0xffff0000, v89
	v_pk_add_f32 v[52:53], v[44:45], v[52:53]
	v_pk_add_f32 v[44:45], v[42:43], v[50:51]
	v_lshl_add_u64 v[42:43], s[6:7], 0, v[104:105]
	v_lshl_add_u64 v[50:51], v[170:171], 1, v[42:43]
	v_cvt_pk_bf16_f32 v42, v46, v47
	v_mul_f32_e32 v47, v47, v47
	v_fmac_f32_e32 v47, v46, v46
	v_mul_f32_e32 v46, v49, v49
	v_fmac_f32_e32 v46, v48, v48
	v_add_f32_e32 v46, v47, v46
	v_mul_f32_e32 v47, v45, v45
	v_fmac_f32_e32 v47, v44, v44
	v_add_f32_e32 v46, v47, v46
	v_mul_f32_e32 v47, v53, v53
	v_fmac_f32_e32 v47, v52, v52
	v_cvt_pk_bf16_f32 v43, v48, v49
	v_add_f32_e32 v54, v47, v46
	s_waitcnt vmcnt(6)
	v_lshlrev_b32_e32 v46, 16, v82
	v_and_b32_e32 v47, 0xffff0000, v82
	v_lshlrev_b32_e32 v48, 16, v83
	v_and_b32_e32 v49, 0xffff0000, v83
	v_pk_add_f32 v[40:41], v[40:41], v[48:49]
	v_pk_add_f32 v[38:39], v[38:39], v[46:47]
	v_lshlrev_b32_e32 v46, 16, v84
	v_and_b32_e32 v47, 0xffff0000, v84
	v_pk_add_f32 v[46:47], v[34:35], v[46:47]
	v_mul_f32_e32 v34, v39, v39
	v_mul_f32_e32 v35, v41, v41
	v_fmac_f32_e32 v34, v38, v38
	v_fmac_f32_e32 v35, v40, v40
	v_lshlrev_b32_e32 v48, 16, v85
	v_and_b32_e32 v49, 0xffff0000, v85
	v_add_f32_e32 v34, v34, v35
	v_mul_f32_e32 v35, v47, v47
	v_pk_add_f32 v[48:49], v[36:37], v[48:49]
	v_fmac_f32_e32 v35, v46, v46
	v_add_f32_e32 v34, v35, v34
	v_mul_f32_e32 v35, v49, v49
	v_fmac_f32_e32 v35, v48, v48
	v_add_f32_e32 v34, v35, v34
	v_add_f32_e32 v34, v54, v34
	v_mov_b32_e32 v35, v34
	s_nop 1
	v_permlane16_swap_b32 v34, v35
	s_nop 1
	v_cvt_pk_bf16_f32 v44, v44, v45
	v_cvt_pk_bf16_f32 v45, v52, v53
	v_cvt_pk_bf16_f32 v36, v38, v39
	v_cvt_pk_bf16_f32 v37, v40, v41
	s_waitcnt lgkmcnt(0)
	v_add_f32_e32 v34, v34, v35
	v_mov_b32_e32 v35, v34
	s_nop 1
	v_permlane32_swap_b32 v34, v35
	s_nop 1
	v_cvt_pk_bf16_f32 v38, v46, v47
	v_cvt_pk_bf16_f32 v39, v48, v49
	global_store_dwordx4 v[50:51], v[42:45], off
	global_store_dwordx4 v[50:51], v[36:39], off offset:256
	s_and_saveexec_b64 s[16:17], s[0:1]
	s_cbranch_execz .LBB0_1162
	s_waitcnt lgkmcnt(0)
	v_add_f32_e32 v36, v34, v35
	s_lshl_b32 s28, s54, 2
	v_lshlrev_b64 v[34:35], 6, v[102:103]
	s_ashr_i32 s29, s28, 31
	v_lshl_add_u64 v[34:35], s[8:9], 0, v[34:35]
	v_lshl_add_u64 v[34:35], s[28:29], 2, v[34:35]
	s_lshl_b32 s12, s50, 2
	v_lshl_add_u64 v[34:35], v[34:35], 0, s[12:13]
	global_store_dword v[34:35], v36, off
;     __device__ __forceinline__ void operator()(const f32x4 (&acc)[2][2][4][2], const Unit& u, int wr, int wc, int fr, int fq) const {
;     ...
;                         const size_t off = (size_t)row * DM + col8;
;                         const u32x4 xi = yall[ai][m][bj];
;                         const f32x4 x0 = (f32x4){bf_lo(xi.x), bf_hi(xi.x), bf_lo(xi.y), bf_hi(xi.y)} + v0, x1 = (f32x4){bf_lo(xi.z), bf_hi(xi.z), bf_lo(xi.w), bf_hi(xi.w)} + v1;
;                         store8(xb + off, x0, x1);
;                         ssacc += (x0[0] * x0[0] + x0[1] * x0[1]) + (x0[2] * x0[2] + x0[3] * x0[3]) + (x1[0] * x1[0] + x1[1] * x1[1]) + (x1[2] * x1[2] + x1[3] * x1[3]);
;                     }
;                 }
;                 if (mode == EP_RESID) {
;                     ssacc += __shfl_xor(ssacc, 16); ssacc += __shfl_xor(ssacc, 32);
;                     if (fq == 0) ss_out[(size_t)row * 16 + u.pn * 4 + wc] = ssacc;
;                 }
.LBB0_1162:
	s_or_b64 exec, exec, s[16:17]
	s_waitcnt vmcnt(7)
	v_lshlrev_b32_e32 v34, 16, v78
	s_waitcnt lgkmcnt(0)
	v_and_b32_e32 v35, 0xffff0000, v78
	v_lshlrev_b32_e32 v36, 16, v79
	v_and_b32_e32 v37, 0xffff0000, v79
	v_pk_add_f32 v[32:33], v[32:33], v[36:37]
	v_pk_add_f32 v[30:31], v[30:31], v[34:35]
	v_lshlrev_b32_e32 v34, 16, v80
	v_and_b32_e32 v35, 0xffff0000, v80
	v_lshlrev_b32_e32 v36, 16, v81
	v_and_b32_e32 v37, 0xffff0000, v81
	v_pk_add_f32 v[36:37], v[28:29], v[36:37]
	v_pk_add_f32 v[28:29], v[26:27], v[34:35]
	v_lshl_add_u64 v[26:27], s[6:7], 0, v[100:101]
	v_lshl_add_u64 v[34:35], v[170:171], 1, v[26:27]
	v_cvt_pk_bf16_f32 v26, v30, v31
	v_mul_f32_e32 v31, v31, v31
	v_fmac_f32_e32 v31, v30, v30
	v_mul_f32_e32 v30, v33, v33
	v_fmac_f32_e32 v30, v32, v32
	v_add_f32_e32 v30, v31, v30
	v_mul_f32_e32 v31, v29, v29
	v_fmac_f32_e32 v31, v28, v28
	v_add_f32_e32 v30, v31, v30
	v_mul_f32_e32 v31, v37, v37
	v_fmac_f32_e32 v31, v36, v36
	v_cvt_pk_bf16_f32 v27, v32, v33
	v_add_f32_e32 v38, v31, v30
	s_waitcnt vmcnt(6)
	v_lshlrev_b32_e32 v30, 16, v74
	v_and_b32_e32 v31, 0xffff0000, v74
	v_lshlrev_b32_e32 v32, 16, v75
	v_and_b32_e32 v33, 0xffff0000, v75
	v_pk_add_f32 v[24:25], v[24:25], v[32:33]
	v_pk_add_f32 v[22:23], v[22:23], v[30:31]
	v_lshlrev_b32_e32 v30, 16, v76
	v_and_b32_e32 v31, 0xffff0000, v76
	v_pk_add_f32 v[30:31], v[18:19], v[30:31]
	v_mul_f32_e32 v18, v23, v23
	v_mul_f32_e32 v19, v25, v25
	v_fmac_f32_e32 v18, v22, v22
	v_fmac_f32_e32 v19, v24, v24
	v_lshlrev_b32_e32 v32, 16, v77
	v_and_b32_e32 v33, 0xffff0000, v77
	v_add_f32_e32 v18, v18, v19
	v_mul_f32_e32 v19, v31, v31
	v_pk_add_f32 v[32:33], v[20:21], v[32:33]
	v_fmac_f32_e32 v19, v30, v30
	v_add_f32_e32 v18, v19, v18
	v_mul_f32_e32 v19, v33, v33
	v_fmac_f32_e32 v19, v32, v32
	v_add_f32_e32 v18, v19, v18
	v_add_f32_e32 v18, v38, v18
	v_mov_b32_e32 v19, v18
	s_nop 1
	v_permlane16_swap_b32 v18, v19
	s_nop 1
	v_cvt_pk_bf16_f32 v28, v28, v29
	v_cvt_pk_bf16_f32 v29, v36, v37
	v_cvt_pk_bf16_f32 v20, v22, v23
	v_cvt_pk_bf16_f32 v21, v24, v25
	s_waitcnt lgkmcnt(0)
	v_add_f32_e32 v18, v18, v19
	v_mov_b32_e32 v19, v18
	s_nop 1
	v_permlane32_swap_b32 v18, v19
	s_nop 1
	v_cvt_pk_bf16_f32 v22, v30, v31
	v_cvt_pk_bf16_f32 v23, v32, v33
	global_store_dwordx4 v[34:35], v[26:29], off
	global_store_dwordx4 v[34:35], v[20:23], off offset:256
	s_and_saveexec_b64 s[16:17], s[0:1]
	s_cbranch_execz .LBB0_1164
	s_waitcnt lgkmcnt(0)
	v_add_f32_e32 v20, v18, v19
	s_lshl_b32 s28, s54, 2
	v_lshlrev_b64 v[18:19], 6, v[96:97]
	s_ashr_i32 s29, s28, 31
	v_lshl_add_u64 v[18:19], s[8:9], 0, v[18:19]
	v_lshl_add_u64 v[18:19], s[28:29], 2, v[18:19]
	s_lshl_b32 s12, s50, 2
	v_lshl_add_u64 v[18:19], v[18:19], 0, s[12:13]
	global_store_dword v[18:19], v20, off
.LBB0_1164:
	s_or_b64 exec, exec, s[16:17]
	s_waitcnt vmcnt(7)
	v_lshlrev_b32_e32 v18, 16, v70
	s_waitcnt lgkmcnt(0)
	v_and_b32_e32 v19, 0xffff0000, v70
	v_lshlrev_b32_e32 v20, 16, v71
	v_and_b32_e32 v21, 0xffff0000, v71
	v_pk_add_f32 v[16:17], v[16:17], v[20:21]
	v_pk_add_f32 v[14:15], v[14:15], v[18:19]
	v_lshlrev_b32_e32 v18, 16, v72
	v_and_b32_e32 v19, 0xffff0000, v72
	v_lshlrev_b32_e32 v20, 16, v73
	v_and_b32_e32 v21, 0xffff0000, v73
	v_pk_add_f32 v[20:21], v[12:13], v[20:21]
	v_pk_add_f32 v[12:13], v[10:11], v[18:19]
	v_lshl_add_u64 v[10:11], s[6:7], 0, v[98:99]
	v_lshl_add_u64 v[18:19], v[170:171], 1, v[10:11]
	v_cvt_pk_bf16_f32 v10, v14, v15
	v_mul_f32_e32 v15, v15, v15
	v_fmac_f32_e32 v15, v14, v14
	v_mul_f32_e32 v14, v17, v17
	v_fmac_f32_e32 v14, v16, v16
	v_add_f32_e32 v14, v15, v14
	v_mul_f32_e32 v15, v13, v13
	v_fmac_f32_e32 v15, v12, v12
	v_add_f32_e32 v14, v15, v14
	v_mul_f32_e32 v15, v21, v21
	v_fmac_f32_e32 v15, v20, v20
	v_cvt_pk_bf16_f32 v11, v16, v17
	v_add_f32_e32 v22, v15, v14
	s_waitcnt vmcnt(6)
	v_lshlrev_b32_e32 v14, 16, v66
	v_and_b32_e32 v15, 0xffff0000, v66
	v_lshlrev_b32_e32 v16, 16, v67
	v_and_b32_e32 v17, 0xffff0000, v67
	v_pk_add_f32 v[8:9], v[8:9], v[16:17]
	v_pk_add_f32 v[6:7], v[6:7], v[14:15]
	v_lshlrev_b32_e32 v14, 16, v68
	v_and_b32_e32 v15, 0xffff0000, v68
	v_pk_add_f32 v[14:15], v[2:3], v[14:15]
	v_mul_f32_e32 v2, v7, v7
	v_mul_f32_e32 v3, v9, v9
	v_fmac_f32_e32 v2, v6, v6
	v_fmac_f32_e32 v3, v8, v8
	v_lshlrev_b32_e32 v16, 16, v69
	v_and_b32_e32 v17, 0xffff0000, v69
	v_add_f32_e32 v2, v2, v3
	v_mul_f32_e32 v3, v15, v15
	v_pk_add_f32 v[16:17], v[4:5], v[16:17]
	v_fmac_f32_e32 v3, v14, v14
	v_add_f32_e32 v2, v3, v2
	v_mul_f32_e32 v3, v17, v17
	v_fmac_f32_e32 v3, v16, v16
	v_add_f32_e32 v2, v3, v2
	v_add_f32_e32 v2, v22, v2
	v_mov_b32_e32 v3, v2
	s_nop 1
	v_permlane16_swap_b32 v2, v3
	s_nop 1
	v_cvt_pk_bf16_f32 v12, v12, v13
	v_cvt_pk_bf16_f32 v13, v20, v21
	v_cvt_pk_bf16_f32 v4, v6, v7
	v_cvt_pk_bf16_f32 v5, v8, v9
	s_waitcnt lgkmcnt(0)
	v_add_f32_e32 v2, v2, v3
	v_mov_b32_e32 v3, v2
	s_nop 1
	v_permlane32_swap_b32 v2, v3
	s_nop 1
	v_cvt_pk_bf16_f32 v6, v14, v15
	v_cvt_pk_bf16_f32 v7, v16, v17
	global_store_dwordx4 v[18:19], v[10:13], off
	global_store_dwordx4 v[18:19], v[4:7], off offset:256
	s_and_saveexec_b64 s[16:17], s[0:1]
	s_cbranch_execz .LBB0_1166
	s_waitcnt lgkmcnt(0)
	v_add_f32_e32 v4, v2, v3
	s_lshl_b32 s28, s54, 2
	v_lshlrev_b64 v[2:3], 6, v[94:95]
	s_ashr_i32 s29, s28, 31
	v_lshl_add_u64 v[2:3], s[8:9], 0, v[2:3]
	v_lshl_add_u64 v[2:3], s[28:29], 2, v[2:3]
	s_lshl_b32 s12, s50, 2
	v_lshl_add_u64 v[2:3], v[2:3], 0, s[12:13]
	global_store_dword v[2:3], v4, off

;     __device__ __forceinline__ void operator()(const f32x4 (&acc)[2][2][4][2], const Unit& u, int wr, int wc, int fr, int fq) const {
;     ...
;         if (rs_n > 0) {
;             f32x4 part[2][4];
; #pragma unroll
;             for (int ai = 0; ai < 2; ++ai)
; #pragma unroll
;                 for (int m = 0; m < 4; ++m) {
;                     part[ai][m] = (f32x4){0.f, 0.f, 0.f, 0.f};
;                     if (4 * fq < rs_n) part[ai][m] = *(const f32x4*)(rs + (size_t)(row0 + ai * HALF + m * 16) * rs_ld + rs_off + 4 * fq);
;                 }
; #pragma unroll
;             for (int ai = 0; ai < 2; ++ai)
; #pragma unroll
;                 for (int m = 0; m < 4; ++m) {
;                     float t = (part[ai][m][0] + part[ai][m][1]) + (part[ai][m][2] + part[ai][m][3]);
;                     t += __shfl_xor(t, 16); t += __shfl_xor(t, 32);
;                     rsc[ai][m] = __builtin_amdgcn_rsqf(t * rs_inv + EPS);
;                 }
;     ...
;                     else if (mode == EP_RELU2) {
; #pragma unroll
;                         for (int e = 0; e < 4; ++e) { float a = fmaxf(v0[e], 0.f), b = fmaxf(v1[e], 0.f); v0[e] = a * a; v1[e] = b * b; }
;                         store8(O + (size_t)row * ldc + col8, v0, v1);
.LBB0_1234:
	v_lshl_add_u32 v174, s49, 8, v167
	v_ashrrev_i32_e32 v175, 31, v174
	v_lshlrev_b64 v[130:131], 6, v[174:175]
	v_lshl_add_u64 v[130:131], v[148:149], 0, v[130:131]
	global_load_dwordx4 v[178:181], v[130:131], off
	v_or_b32_e32 v168, 16, v174
	v_ashrrev_i32_e32 v169, 31, v168
	v_lshlrev_b64 v[130:131], 6, v[168:169]
	v_lshl_add_u64 v[130:131], v[148:149], 0, v[130:131]
	global_load_dwordx4 v[182:185], v[130:131], off
	v_or_b32_e32 v164, 32, v174
	v_ashrrev_i32_e32 v165, 31, v164
	v_lshlrev_b64 v[130:131], 6, v[164:165]
	v_lshl_add_u64 v[130:131], v[148:149], 0, v[130:131]
	global_load_dwordx4 v[186:189], v[130:131], off
	v_or_b32_e32 v162, 48, v174
	v_ashrrev_i32_e32 v163, 31, v162
	v_lshlrev_b64 v[130:131], 6, v[162:163]
	v_lshl_add_u64 v[130:131], v[148:149], 0, v[130:131]
	global_load_dwordx4 v[190:193], v[130:131], off
	v_add_u32_e32 v160, 0x80, v174
	v_ashrrev_i32_e32 v161, 31, v160
	v_lshlrev_b64 v[130:131], 6, v[160:161]
	v_lshl_add_u64 v[130:131], v[148:149], 0, v[130:131]
	global_load_dwordx4 v[196:199], v[130:131], off
	v_add_u32_e32 v158, 0x90, v174
	v_ashrrev_i32_e32 v159, 31, v158
	v_lshlrev_b64 v[130:131], 6, v[158:159]
	v_add_u32_e32 v156, 0xa0, v174
	v_lshl_add_u64 v[130:131], v[148:149], 0, v[130:131]
	v_ashrrev_i32_e32 v157, 31, v156
	global_load_dwordx4 v[138:141], v[130:131], off
	v_lshlrev_b64 v[130:131], 6, v[156:157]
	v_add_u32_e32 v154, 0xb0, v174
	v_lshl_add_u64 v[130:131], v[148:149], 0, v[130:131]
	v_ashrrev_i32_e32 v155, 31, v154
	global_load_dwordx4 v[134:137], v[130:131], off
	v_lshlrev_b64 v[130:131], 6, v[154:155]
	v_lshl_add_u64 v[130:131], v[148:149], 0, v[130:131]
	global_load_dwordx4 v[130:133], v[130:131], off
	s_mov_b64 s[16:17], -1
	s_andn2_b64 vcc, exec, s[0:1]
	s_waitcnt vmcnt(0)
	v_mov_b32_e32 v200, v179
	v_mov_b32_e32 v201, v180
	v_mov_b32_e32 v179, v181
	v_pk_add_f32 v[178:179], v[200:201], v[178:179]
	v_mov_b32_e32 v180, v183
	v_add_f32_e32 v166, v178, v179
	v_mov_b32_e32 v170, v166
	s_nop 1
	v_permlane16_swap_b32 v166, v170
	s_nop 1
	v_mov_b32_e32 v181, v184
	v_mov_b32_e32 v183, v185
	v_pk_add_f32 v[180:181], v[180:181], v[182:183]
	s_waitcnt lgkmcnt(0)
	v_add_f32_e32 v166, v166, v170
	v_mov_b32_e32 v170, v166
	s_nop 1
	v_permlane32_swap_b32 v166, v170
	s_nop 1
	s_waitcnt lgkmcnt(0)
	v_add_f32_e32 v166, v166, v170
	v_fmamk_f32 v166, v166, 0x3a800000, v195
	v_rsq_f32_e32 v178, v166
	v_add_f32_e32 v166, v180, v181
	v_mov_b32_e32 v170, v166
	s_nop 1
	v_permlane16_swap_b32 v166, v170
	s_nop 1
	v_mov_b32_e32 v180, v187
	v_mov_b32_e32 v181, v188
	v_mov_b32_e32 v187, v189
	v_pk_add_f32 v[180:181], v[180:181], v[186:187]
	s_waitcnt lgkmcnt(0)
	v_add_f32_e32 v166, v166, v170
	v_mov_b32_e32 v170, v166
	s_nop 1
	v_permlane32_swap_b32 v166, v170
	s_nop 1
	s_waitcnt lgkmcnt(0)
	v_add_f32_e32 v166, v166, v170
	v_fmamk_f32 v166, v166, 0x3a800000, v195
	v_rsq_f32_e32 v176, v166
	v_add_f32_e32 v166, v180, v181
	v_mov_b32_e32 v170, v166
	s_nop 1
	v_permlane16_swap_b32 v166, v170
	s_nop 1
	v_mov_b32_e32 v180, v191
	v_mov_b32_e32 v181, v192
	v_mov_b32_e32 v191, v193
	v_pk_add_f32 v[180:181], v[180:181], v[190:191]
	s_waitcnt lgkmcnt(0)
	v_add_f32_e32 v166, v166, v170
	v_mov_b32_e32 v170, v166
	s_nop 1
	v_permlane32_swap_b32 v166, v170
	s_nop 1
	v_pk_mul_f32 v[106:107], v[106:107], v[176:177] op_sel_hi:[1,0]
	v_pk_mul_f32 v[112:113], v[112:113], v[176:177] op_sel_hi:[1,0]
	v_max_f32_e32 v106, 0, v106
	v_max_f32_e32 v107, 0, v107
	s_waitcnt lgkmcnt(0)
	v_add_f32_e32 v166, v166, v170
	v_fmamk_f32 v166, v166, 0x3a800000, v195
	v_rsq_f32_e32 v172, v166
	v_add_f32_e32 v166, v180, v181
	v_mov_b32_e32 v170, v166
	s_nop 1
	v_permlane16_swap_b32 v166, v170
	s_nop 1
	v_mov_b32_e32 v180, v197
	v_mov_b32_e32 v181, v198
	v_mov_b32_e32 v197, v199
	v_pk_add_f32 v[180:181], v[180:181], v[196:197]
	s_waitcnt lgkmcnt(0)
	v_add_f32_e32 v166, v166, v170
	v_mov_b32_e32 v170, v166
	s_nop 1
	v_permlane32_swap_b32 v166, v170
	s_nop 1
	v_pk_mul_f32 v[110:111], v[110:111], v[176:177] op_sel_hi:[1,0]
	v_pk_mul_f32 v[108:109], v[108:109], v[176:177] op_sel_hi:[1,0]
	v_max_f32_e32 v110, 0, v110
	v_max_f32_e32 v111, 0, v111
	s_waitcnt lgkmcnt(0)
	v_add_f32_e32 v166, v166, v170
	v_fmamk_f32 v166, v166, 0x3a800000, v195
	v_rsq_f32_e32 v170, v166
	v_add_f32_e32 v166, v180, v181
	v_mov_b32_e32 v179, v166
	s_nop 1
	v_permlane16_swap_b32 v166, v179
	s_nop 1
	v_mov_b32_e32 v180, v139
	v_mov_b32_e32 v181, v140
	v_mov_b32_e32 v139, v141
	v_mov_b32_e32 v140, v135
	s_waitcnt lgkmcnt(0)
	v_add_f32_e32 v166, v166, v179
	v_mov_b32_e32 v179, v166
	s_nop 1
	v_permlane32_swap_b32 v166, v179
	s_nop 1
	v_mov_b32_e32 v141, v136
	v_mov_b32_e32 v135, v137
	v_mov_b32_e32 v136, v131
	v_mov_b32_e32 v137, v132
	s_waitcnt lgkmcnt(0)
;     __device__ __forceinline__ void operator()(const f32x4 (&acc)[2][2][4][2], const Unit& u, int wr, int wc, int fr, int fq) const {
;     ...
; #pragma unroll
;             for (int ai = 0; ai < 2; ++ai)
; #pragma unroll
;                 for (int m = 0; m < 4; ++m) {
;                     float t = (part[ai][m][0] + part[ai][m][1]) + (part[ai][m][2] + part[ai][m][3]);
;                     t += __shfl_xor(t, 16); t += __shfl_xor(t, 32);
;                     rsc[ai][m] = __builtin_amdgcn_rsqf(t * rs_inv + EPS);
;                 }
;     ...
;                     else if (mode == EP_RELU2) {
; #pragma unroll
;                         for (int e = 0; e < 4; ++e) { float a = fmaxf(v0[e], 0.f), b = fmaxf(v1[e], 0.f); v0[e] = a * a; v1[e] = b * b; }
;                         store8(O + (size_t)row * ldc + col8, v0, v1);
	v_pk_mul_f32 v[122:123], v[122:123], v[178:179] op_sel_hi:[1,0]
	v_mov_b32_e32 v131, v133
	v_pk_mul_f32 v[128:129], v[128:129], v[178:179] op_sel_hi:[1,0]
	v_max_f32_e32 v122, 0, v122
	v_max_f32_e32 v123, 0, v123
	v_pk_add_f32 v[130:131], v[136:137], v[130:131]
	v_lshl_or_b32 v132, s48, 8, v173
	v_pk_mul_f32 v[126:127], v[126:127], v[178:179] op_sel_hi:[1,0]
	v_pk_mul_f32 v[124:125], v[124:125], v[178:179] op_sel_hi:[1,0]
	v_pk_mul_f32 v[136:137], v[122:123], v[122:123]
	v_max_f32_e32 v122, 0, v128
	v_max_f32_e32 v123, 0, v129
	v_max_f32_e32 v126, 0, v126
	v_max_f32_e32 v127, 0, v127
	v_max_f32_e32 v124, 0, v124
	v_max_f32_e32 v125, 0, v125
	v_pk_mul_f32 v[128:129], v[122:123], v[122:123]
	v_lshlrev_b64 v[122:123], 13, v[174:175]
	v_ashrrev_i32_e32 v133, 31, v132
	v_pk_add_f32 v[134:135], v[140:141], v[134:135]
	v_pk_mul_f32 v[126:127], v[126:127], v[126:127]
	v_pk_mul_f32 v[140:141], v[124:125], v[124:125]
	v_lshl_add_u64 v[124:125], s[6:7], 0, v[122:123]
	v_lshlrev_b64 v[122:123], 1, v[132:133]
	v_pk_mul_f32 v[114:115], v[114:115], v[178:179] op_sel_hi:[1,0]
	v_lshl_add_u64 v[132:133], v[124:125], 0, v[122:123]
	v_cvt_pk_bf16_f32 v124, v126, v127
	v_cvt_pk_bf16_f32 v125, v128, v129
	v_cvt_pk_bf16_f32 v126, v136, v137
	v_cvt_pk_bf16_f32 v127, v140, v141
	v_pk_mul_f32 v[120:121], v[120:121], v[178:179] op_sel_hi:[1,0]
	v_pk_mul_f32 v[118:119], v[118:119], v[178:179] op_sel_hi:[1,0]
	v_pk_mul_f32 v[116:117], v[116:117], v[178:179] op_sel_hi:[1,0]
	v_max_f32_e32 v114, 0, v114
	v_max_f32_e32 v115, 0, v115
	global_store_dwordx4 v[132:133], v[124:127], off
	v_max_f32_e32 v118, 0, v118
	v_max_f32_e32 v119, 0, v119
	v_pk_mul_f32 v[124:125], v[114:115], v[114:115]
	v_max_f32_e32 v114, 0, v120
	v_max_f32_e32 v116, 0, v116
	v_max_f32_e32 v115, 0, v121
	v_max_f32_e32 v117, 0, v117
	v_pk_mul_f32 v[118:119], v[118:119], v[118:119]
	v_pk_mul_f32 v[120:121], v[114:115], v[114:115]
	v_pk_mul_f32 v[126:127], v[116:117], v[116:117]
	v_cvt_pk_bf16_f32 v114, v118, v119
	v_cvt_pk_bf16_f32 v115, v120, v121
	v_cvt_pk_bf16_f32 v116, v124, v125
	v_cvt_pk_bf16_f32 v117, v126, v127
	global_store_dwordx4 v[132:133], v[114:117], off offset:256
	v_max_f32_e32 v108, 0, v108
	v_max_f32_e32 v109, 0, v109
	v_pk_mul_f32 v[114:115], v[106:107], v[106:107]
	v_max_f32_e32 v106, 0, v112
	v_max_f32_e32 v107, 0, v113
	v_pk_mul_f32 v[112:113], v[106:107], v[106:107]
	v_lshlrev_b64 v[106:107], 13, v[168:169]
	v_pk_mul_f32 v[110:111], v[110:111], v[110:111]
	v_pk_mul_f32 v[116:117], v[108:109], v[108:109]
	v_lshl_add_u64 v[106:107], s[6:7], 0, v[106:107]
	v_pk_mul_f32 v[98:99], v[98:99], v[176:177] op_sel_hi:[1,0]
	v_lshl_add_u64 v[118:119], v[106:107], 0, v[122:123]
	v_cvt_pk_bf16_f32 v106, v110, v111
	v_cvt_pk_bf16_f32 v107, v112, v113
	v_cvt_pk_bf16_f32 v108, v114, v115
	v_cvt_pk_bf16_f32 v109, v116, v117
	v_pk_mul_f32 v[104:105], v[104:105], v[176:177] op_sel_hi:[1,0]
	v_pk_mul_f32 v[102:103], v[102:103], v[176:177] op_sel_hi:[1,0]
	v_pk_mul_f32 v[100:101], v[100:101], v[176:177] op_sel_hi:[1,0]
	v_max_f32_e32 v98, 0, v98
	v_max_f32_e32 v99, 0, v99
	global_store_dwordx4 v[118:119], v[106:109], off
	v_max_f32_e32 v102, 0, v102
	v_max_f32_e32 v103, 0, v103
	v_pk_mul_f32 v[106:107], v[98:99], v[98:99]
	v_max_f32_e32 v98, 0, v104
	v_max_f32_e32 v100, 0, v100
	v_max_f32_e32 v99, 0, v105
	v_max_f32_e32 v101, 0, v101
	v_pk_mul_f32 v[102:103], v[102:103], v[102:103]
	v_pk_mul_f32 v[104:105], v[98:99], v[98:99]
	v_pk_mul_f32 v[108:109], v[100:101], v[100:101]
	v_pk_mul_f32 v[90:91], v[90:91], v[172:173] op_sel_hi:[1,0]
	v_pk_add_f32 v[138:139], v[180:181], v[138:139]
	v_cvt_pk_bf16_f32 v98, v102, v103
	v_cvt_pk_bf16_f32 v99, v104, v105
	v_cvt_pk_bf16_f32 v100, v106, v107
	v_cvt_pk_bf16_f32 v101, v108, v109
	v_pk_mul_f32 v[96:97], v[96:97], v[172:173] op_sel_hi:[1,0]
	v_pk_mul_f32 v[94:95], v[94:95], v[172:173] op_sel_hi:[1,0]
	v_pk_mul_f32 v[92:93], v[92:93], v[172:173] op_sel_hi:[1,0]
	v_max_f32_e32 v90, 0, v90
	v_max_f32_e32 v91, 0, v91
	v_add_f32_e32 v138, v138, v139
	global_store_dwordx4 v[118:119], v[98:101], off offset:256
	v_max_f32_e32 v94, 0, v94
	v_max_f32_e32 v95, 0, v95
	v_lshlrev_b64 v[98:99], 13, v[164:165]
	v_pk_mul_f32 v[100:101], v[90:91], v[90:91]
	v_max_f32_e32 v90, 0, v96
	v_max_f32_e32 v92, 0, v92
	v_max_f32_e32 v91, 0, v97
	v_max_f32_e32 v93, 0, v93
	v_mov_b32_e32 v139, v138
	s_nop 1
	v_permlane16_swap_b32 v138, v139
	s_nop 1
	v_pk_mul_f32 v[94:95], v[94:95], v[94:95]
	v_pk_mul_f32 v[96:97], v[90:91], v[90:91]
	v_pk_mul_f32 v[102:103], v[92:93], v[92:93]
	v_lshl_add_u64 v[90:91], s[6:7], 0, v[98:99]
	v_pk_mul_f32 v[82:83], v[82:83], v[172:173] op_sel_hi:[1,0]
	v_lshl_add_u64 v[98:99], v[90:91], 0, v[122:123]
	v_cvt_pk_bf16_f32 v90, v94, v95
	v_cvt_pk_bf16_f32 v91, v96, v97
	v_cvt_pk_bf16_f32 v92, v100, v101
	v_cvt_pk_bf16_f32 v93, v102, v103
	v_pk_mul_f32 v[88:89], v[88:89], v[172:173] op_sel_hi:[1,0]
	v_pk_mul_f32 v[86:87], v[86:87], v[172:173] op_sel_hi:[1,0]
	v_pk_mul_f32 v[84:85], v[84:85], v[172:173] op_sel_hi:[1,0]
	v_max_f32_e32 v82, 0, v82
	v_max_f32_e32 v83, 0, v83
	global_store_dwordx4 v[98:99], v[90:93], off
	v_max_f32_e32 v86, 0, v86
	v_max_f32_e32 v87, 0, v87
	v_pk_mul_f32 v[90:91], v[82:83], v[82:83]
	v_max_f32_e32 v82, 0, v88
	v_max_f32_e32 v84, 0, v84
	v_max_f32_e32 v83, 0, v89
	v_max_f32_e32 v85, 0, v85
	v_pk_mul_f32 v[86:87], v[86:87], v[86:87]
	v_pk_mul_f32 v[88:89], v[82:83], v[82:83]
	v_pk_mul_f32 v[92:93], v[84:85], v[84:85]
	v_pk_mul_f32 v[74:75], v[74:75], v[170:171] op_sel_hi:[1,0]
	v_add_f32_e32 v166, v166, v179
	v_cvt_pk_bf16_f32 v82, v86, v87
	v_cvt_pk_bf16_f32 v83, v88, v89
	v_cvt_pk_bf16_f32 v84, v90, v91
	v_cvt_pk_bf16_f32 v85, v92, v93
	v_pk_mul_f32 v[80:81], v[80:81], v[170:171] op_sel_hi:[1,0]
	v_max_f32_e32 v74, 0, v74
	v_max_f32_e32 v75, 0, v75
	v_fmamk_f32 v166, v166, 0x3a800000, v195
	s_waitcnt lgkmcnt(0)
;     __device__ __forceinline__ void operator()(const f32x4 (&acc)[2][2][4][2], const Unit& u, int wr, int wc, int fr, int fq) const {
;     ...
; #pragma unroll
;             for (int ai = 0; ai < 2; ++ai)
; #pragma unroll
;                 for (int m = 0; m < 4; ++m) {
;                     float t = (part[ai][m][0] + part[ai][m][1]) + (part[ai][m][2] + part[ai][m][3]);
;                     t += __shfl_xor(t, 16); t += __shfl_xor(t, 32);
;                     rsc[ai][m] = __builtin_amdgcn_rsqf(t * rs_inv + EPS);
;                 }
;     ...
;                     else if (mode == EP_RELU2) {
; #pragma unroll
;                         for (int e = 0; e < 4; ++e) { float a = fmaxf(v0[e], 0.f), b = fmaxf(v1[e], 0.f); v0[e] = a * a; v1[e] = b * b; }
;                         store8(O + (size_t)row * ldc + col8, v0, v1);
	v_add_f32_e32 v138, v138, v139
	global_store_dwordx4 v[98:99], v[82:85], off offset:256
	v_pk_mul_f32 v[78:79], v[78:79], v[170:171] op_sel_hi:[1,0]
	v_pk_mul_f32 v[76:77], v[76:77], v[170:171] op_sel_hi:[1,0]
	v_pk_mul_f32 v[82:83], v[74:75], v[74:75]
	v_max_f32_e32 v74, 0, v80
	v_max_f32_e32 v75, 0, v81
	v_rsq_f32_e32 v166, v166
	v_mov_b32_e32 v139, v138
	s_nop 1
	v_permlane32_swap_b32 v138, v139
	s_nop 1
	v_add_f32_e32 v134, v134, v135
	v_max_f32_e32 v78, 0, v78
	v_max_f32_e32 v79, 0, v79
	v_max_f32_e32 v76, 0, v76
	v_max_f32_e32 v77, 0, v77
	v_pk_mul_f32 v[80:81], v[74:75], v[74:75]
	v_lshlrev_b64 v[74:75], 13, v[162:163]
	v_mov_b32_e32 v135, v134
	s_nop 1
	v_permlane16_swap_b32 v134, v135
	s_nop 1
	v_pk_mul_f32 v[78:79], v[78:79], v[78:79]
	v_pk_mul_f32 v[84:85], v[76:77], v[76:77]
	v_lshl_add_u64 v[74:75], s[6:7], 0, v[74:75]
	v_pk_mul_f32 v[66:67], v[66:67], v[170:171] op_sel_hi:[1,0]
	v_lshl_add_u64 v[86:87], v[74:75], 0, v[122:123]
	v_cvt_pk_bf16_f32 v74, v78, v79
	v_cvt_pk_bf16_f32 v75, v80, v81
	v_cvt_pk_bf16_f32 v76, v82, v83
	v_cvt_pk_bf16_f32 v77, v84, v85
	v_pk_mul_f32 v[72:73], v[72:73], v[170:171] op_sel_hi:[1,0]
	v_pk_mul_f32 v[70:71], v[70:71], v[170:171] op_sel_hi:[1,0]
	v_pk_mul_f32 v[68:69], v[68:69], v[170:171] op_sel_hi:[1,0]
	v_max_f32_e32 v66, 0, v66
	v_max_f32_e32 v67, 0, v67
	global_store_dwordx4 v[86:87], v[74:77], off
	v_max_f32_e32 v70, 0, v70
	v_max_f32_e32 v71, 0, v71
	v_pk_mul_f32 v[74:75], v[66:67], v[66:67]
	v_max_f32_e32 v66, 0, v72
	v_max_f32_e32 v68, 0, v68
	v_max_f32_e32 v67, 0, v73
	v_max_f32_e32 v69, 0, v69
	v_pk_mul_f32 v[70:71], v[70:71], v[70:71]
	v_pk_mul_f32 v[72:73], v[66:67], v[66:67]
	v_pk_mul_f32 v[76:77], v[68:69], v[68:69]
	v_pk_mul_f32 v[58:59], v[58:59], v[166:167] op_sel_hi:[1,0]
	s_waitcnt lgkmcnt(1)
	v_add_f32_e32 v138, v138, v139
	v_cvt_pk_bf16_f32 v66, v70, v71
	v_cvt_pk_bf16_f32 v67, v72, v73
	v_cvt_pk_bf16_f32 v68, v74, v75
	v_cvt_pk_bf16_f32 v69, v76, v77
	v_pk_mul_f32 v[64:65], v[64:65], v[166:167] op_sel_hi:[1,0]
	v_max_f32_e32 v58, 0, v58
	v_max_f32_e32 v59, 0, v59
	v_fmamk_f32 v138, v138, 0x3a800000, v195
	s_waitcnt lgkmcnt(0)
	v_add_f32_e32 v134, v134, v135
	v_add_f32_e32 v130, v130, v131
	global_store_dwordx4 v[86:87], v[66:69], off offset:256
	v_pk_mul_f32 v[62:63], v[62:63], v[166:167] op_sel_hi:[1,0]
	v_pk_mul_f32 v[60:61], v[60:61], v[166:167] op_sel_hi:[1,0]
	v_pk_mul_f32 v[66:67], v[58:59], v[58:59]
	v_max_f32_e32 v58, 0, v64
	v_max_f32_e32 v59, 0, v65
	v_rsq_f32_e32 v138, v138
	v_mov_b32_e32 v135, v134
	s_nop 1
	v_permlane32_swap_b32 v134, v135
	s_nop 1
	v_mov_b32_e32 v131, v130
	s_nop 1
	v_permlane16_swap_b32 v130, v131
	s_nop 1
	v_max_f32_e32 v62, 0, v62
	v_max_f32_e32 v63, 0, v63
	v_max_f32_e32 v60, 0, v60
	v_max_f32_e32 v61, 0, v61
	v_pk_mul_f32 v[64:65], v[58:59], v[58:59]
	v_lshlrev_b64 v[58:59], 13, v[160:161]
	v_pk_mul_f32 v[62:63], v[62:63], v[62:63]
	v_pk_mul_f32 v[68:69], v[60:61], v[60:61]
	v_lshl_add_u64 v[58:59], s[6:7], 0, v[58:59]
	v_pk_mul_f32 v[50:51], v[50:51], v[166:167] op_sel_hi:[1,0]
	v_lshl_add_u64 v[70:71], v[58:59], 0, v[122:123]
	v_cvt_pk_bf16_f32 v58, v62, v63
	v_cvt_pk_bf16_f32 v59, v64, v65
	v_cvt_pk_bf16_f32 v60, v66, v67
	v_cvt_pk_bf16_f32 v61, v68, v69
	v_pk_mul_f32 v[56:57], v[56:57], v[166:167] op_sel_hi:[1,0]
	v_pk_mul_f32 v[54:55], v[54:55], v[166:167] op_sel_hi:[1,0]
	v_pk_mul_f32 v[52:53], v[52:53], v[166:167] op_sel_hi:[1,0]
	v_max_f32_e32 v50, 0, v50
	v_max_f32_e32 v51, 0, v51
	global_store_dwordx4 v[70:71], v[58:61], off
	v_max_f32_e32 v54, 0, v54
	v_max_f32_e32 v55, 0, v55
	v_pk_mul_f32 v[58:59], v[50:51], v[50:51]
	v_max_f32_e32 v50, 0, v56
	v_max_f32_e32 v52, 0, v52
	v_max_f32_e32 v51, 0, v57
	v_max_f32_e32 v53, 0, v53
	v_pk_mul_f32 v[54:55], v[54:55], v[54:55]
	v_pk_mul_f32 v[56:57], v[50:51], v[50:51]
	v_pk_mul_f32 v[60:61], v[52:53], v[52:53]
	v_pk_mul_f32 v[42:43], v[42:43], v[138:139] op_sel_hi:[1,0]
	s_waitcnt lgkmcnt(1)
	v_add_f32_e32 v134, v134, v135
	s_waitcnt lgkmcnt(0)
	v_add_f32_e32 v130, v130, v131
	v_cvt_pk_bf16_f32 v50, v54, v55
	v_cvt_pk_bf16_f32 v51, v56, v57
	v_cvt_pk_bf16_f32 v52, v58, v59
	v_cvt_pk_bf16_f32 v53, v60, v61
	v_pk_mul_f32 v[48:49], v[48:49], v[138:139] op_sel_hi:[1,0]
	v_max_f32_e32 v42, 0, v42
	v_max_f32_e32 v43, 0, v43
	v_fmamk_f32 v134, v134, 0x3a800000, v195
	v_mov_b32_e32 v131, v130
	s_nop 1
	v_permlane32_swap_b32 v130, v131
	s_nop 1
	global_store_dwordx4 v[70:71], v[50:53], off offset:256
	v_pk_mul_f32 v[46:47], v[46:47], v[138:139] op_sel_hi:[1,0]
	v_pk_mul_f32 v[44:45], v[44:45], v[138:139] op_sel_hi:[1,0]
	v_pk_mul_f32 v[50:51], v[42:43], v[42:43]
	v_max_f32_e32 v42, 0, v48
	v_max_f32_e32 v43, 0, v49
	v_rsq_f32_e32 v134, v134
	v_max_f32_e32 v46, 0, v46
	v_max_f32_e32 v47, 0, v47
	v_max_f32_e32 v44, 0, v44
	v_max_f32_e32 v45, 0, v45
	v_pk_mul_f32 v[48:49], v[42:43], v[42:43]
	v_lshlrev_b64 v[42:43], 13, v[158:159]
	v_pk_mul_f32 v[46:47], v[46:47], v[46:47]
	v_pk_mul_f32 v[52:53], v[44:45], v[44:45]
	v_lshl_add_u64 v[42:43], s[6:7], 0, v[42:43]
	v_pk_mul_f32 v[34:35], v[34:35], v[138:139] op_sel_hi:[1,0]
	v_lshl_add_u64 v[54:55], v[42:43], 0, v[122:123]
	v_cvt_pk_bf16_f32 v42, v46, v47
	v_cvt_pk_bf16_f32 v43, v48, v49
	v_cvt_pk_bf16_f32 v44, v50, v51
	v_cvt_pk_bf16_f32 v45, v52, v53
	v_pk_mul_f32 v[40:41], v[40:41], v[138:139] op_sel_hi:[1,0]
	v_pk_mul_f32 v[38:39], v[38:39], v[138:139] op_sel_hi:[1,0]
	v_pk_mul_f32 v[36:37], v[36:37], v[138:139] op_sel_hi:[1,0]
	v_max_f32_e32 v34, 0, v34
	v_max_f32_e32 v35, 0, v35
	global_store_dwordx4 v[54:55], v[42:45], off
	v_max_f32_e32 v38, 0, v38
	v_max_f32_e32 v39, 0, v39
	v_pk_mul_f32 v[42:43], v[34:35], v[34:35]
	v_max_f32_e32 v34, 0, v40
	v_max_f32_e32 v36, 0, v36
	v_max_f32_e32 v35, 0, v41
	v_max_f32_e32 v37, 0, v37
	s_waitcnt lgkmcnt(0)
; #define PG8_BAR __builtin_amdgcn_s_barrier()
;     __device__ __forceinline__ void operator()(const f32x4 (&acc)[2][2][4][2], const Unit& u, int wr, int wc, int fr, int fq) const {
;     ...
;                     f32x4 v0 = acc[ai][bj][m][0] * rs1, v1 = acc[ai][bj][m][1] * rs1;
;                     if (mode == EP_PLAIN) { store8(O + (size_t)row * ldc + col8, v0, v1); }
;                     else if (mode == EP_RELU2) {
; #pragma unroll
;                         for (int e = 0; e < 4; ++e) { float a = fmaxf(v0[e], 0.f), b = fmaxf(v1[e], 0.f); v0[e] = a * a; v1[e] = b * b; }
;                         store8(O + (size_t)row * ldc + col8, v0, v1);
; template <class Epi, class Sched, bool ALIGN_EPI = false, bool SP2 = false>
; __device__ __forceinline__ void gemm_phase(PG8_LAS unsigned char* lds, const Gemm g, const Sched& S, const Epi& E, int wv) {
;     ...
;         if (!has_next) break;
; #pragma unroll
;         for (int a = 0; a < 2; ++a)
; #pragma unroll
;             for (int b = 0; b < 2; ++b)
; #pragma unroll
;                 for (int m = 0; m < 4; ++m)
; #pragma unroll
;                     for (int n = 0; n < 2; ++n) acc[a][b][m][n] = (f32x4){0.f, 0.f, 0.f, 0.f};
;         cur = nxt; cA = nA; cB = nB; ++ui;
;         if constexpr (ALIGN_EPI) { if (wr == 1) PG8_BAR; }
	v_add_f32_e32 v130, v130, v131
	v_pk_mul_f32 v[38:39], v[38:39], v[38:39]
	v_pk_mul_f32 v[40:41], v[34:35], v[34:35]
	v_pk_mul_f32 v[44:45], v[36:37], v[36:37]
	v_pk_mul_f32 v[26:27], v[26:27], v[134:135] op_sel_hi:[1,0]
	v_fmamk_f32 v130, v130, 0x3a800000, v195
	v_cvt_pk_bf16_f32 v34, v38, v39
	v_cvt_pk_bf16_f32 v35, v40, v41
	v_cvt_pk_bf16_f32 v36, v42, v43
	v_cvt_pk_bf16_f32 v37, v44, v45
	v_pk_mul_f32 v[32:33], v[32:33], v[134:135] op_sel_hi:[1,0]
	v_pk_mul_f32 v[30:31], v[30:31], v[134:135] op_sel_hi:[1,0]
	v_pk_mul_f32 v[28:29], v[28:29], v[134:135] op_sel_hi:[1,0]
	v_max_f32_e32 v26, 0, v26
	v_max_f32_e32 v27, 0, v27
	v_rsq_f32_e32 v130, v130
	global_store_dwordx4 v[54:55], v[34:37], off offset:256
	v_max_f32_e32 v30, 0, v30
	v_max_f32_e32 v31, 0, v31
	v_lshlrev_b64 v[34:35], 13, v[156:157]
	v_pk_mul_f32 v[36:37], v[26:27], v[26:27]
	v_max_f32_e32 v26, 0, v32
	v_max_f32_e32 v28, 0, v28
	v_max_f32_e32 v27, 0, v33
	v_max_f32_e32 v29, 0, v29
	v_pk_mul_f32 v[30:31], v[30:31], v[30:31]
	v_pk_mul_f32 v[32:33], v[26:27], v[26:27]
	v_pk_mul_f32 v[38:39], v[28:29], v[28:29]
	v_lshl_add_u64 v[26:27], s[6:7], 0, v[34:35]
	v_pk_mul_f32 v[18:19], v[18:19], v[134:135] op_sel_hi:[1,0]
	v_lshl_add_u64 v[34:35], v[26:27], 0, v[122:123]
	v_cvt_pk_bf16_f32 v26, v30, v31
	v_cvt_pk_bf16_f32 v27, v32, v33
	v_cvt_pk_bf16_f32 v28, v36, v37
	v_cvt_pk_bf16_f32 v29, v38, v39
	v_pk_mul_f32 v[24:25], v[24:25], v[134:135] op_sel_hi:[1,0]
	v_pk_mul_f32 v[22:23], v[22:23], v[134:135] op_sel_hi:[1,0]
	v_pk_mul_f32 v[20:21], v[20:21], v[134:135] op_sel_hi:[1,0]
	v_max_f32_e32 v18, 0, v18
	v_max_f32_e32 v19, 0, v19
	global_store_dwordx4 v[34:35], v[26:29], off
	v_max_f32_e32 v22, 0, v22
	v_max_f32_e32 v23, 0, v23
	v_pk_mul_f32 v[26:27], v[18:19], v[18:19]
	v_max_f32_e32 v18, 0, v24
	v_max_f32_e32 v20, 0, v20
	v_max_f32_e32 v19, 0, v25
	v_max_f32_e32 v21, 0, v21
	v_pk_mul_f32 v[22:23], v[22:23], v[22:23]
	v_pk_mul_f32 v[24:25], v[18:19], v[18:19]
	v_pk_mul_f32 v[28:29], v[20:21], v[20:21]
	v_pk_mul_f32 v[10:11], v[10:11], v[130:131] op_sel_hi:[1,0]
	v_cvt_pk_bf16_f32 v18, v22, v23
	v_cvt_pk_bf16_f32 v19, v24, v25
	v_cvt_pk_bf16_f32 v20, v26, v27
	v_cvt_pk_bf16_f32 v21, v28, v29
	v_pk_mul_f32 v[16:17], v[16:17], v[130:131] op_sel_hi:[1,0]
	v_max_f32_e32 v10, 0, v10
	v_max_f32_e32 v11, 0, v11
	global_store_dwordx4 v[34:35], v[18:21], off offset:256
	v_pk_mul_f32 v[14:15], v[14:15], v[130:131] op_sel_hi:[1,0]
	v_pk_mul_f32 v[12:13], v[12:13], v[130:131] op_sel_hi:[1,0]
	v_pk_mul_f32 v[18:19], v[10:11], v[10:11]
	v_max_f32_e32 v10, 0, v16
	v_max_f32_e32 v11, 0, v17
	v_max_f32_e32 v14, 0, v14
	v_max_f32_e32 v15, 0, v15
	v_max_f32_e32 v12, 0, v12
	v_max_f32_e32 v13, 0, v13
	v_pk_mul_f32 v[16:17], v[10:11], v[10:11]
	v_lshlrev_b64 v[10:11], 13, v[154:155]
	v_pk_mul_f32 v[14:15], v[14:15], v[14:15]
	v_pk_mul_f32 v[20:21], v[12:13], v[12:13]
	v_lshl_add_u64 v[10:11], s[6:7], 0, v[10:11]
	v_pk_mul_f32 v[2:3], v[2:3], v[130:131] op_sel_hi:[1,0]
	v_lshl_add_u64 v[22:23], v[10:11], 0, v[122:123]
	v_cvt_pk_bf16_f32 v10, v14, v15
	v_cvt_pk_bf16_f32 v11, v16, v17
	v_cvt_pk_bf16_f32 v12, v18, v19
	v_cvt_pk_bf16_f32 v13, v20, v21
	v_pk_mul_f32 v[8:9], v[8:9], v[130:131] op_sel_hi:[1,0]
	v_pk_mul_f32 v[6:7], v[6:7], v[130:131] op_sel_hi:[1,0]
	v_pk_mul_f32 v[4:5], v[4:5], v[130:131] op_sel_hi:[1,0]
	v_max_f32_e32 v2, 0, v2
	v_max_f32_e32 v3, 0, v3
	global_store_dwordx4 v[22:23], v[10:13], off
	v_max_f32_e32 v6, 0, v6
	v_max_f32_e32 v7, 0, v7
	v_pk_mul_f32 v[10:11], v[2:3], v[2:3]
	v_max_f32_e32 v2, 0, v8
	v_max_f32_e32 v4, 0, v4
	v_max_f32_e32 v3, 0, v9
	v_max_f32_e32 v5, 0, v5
	v_pk_mul_f32 v[6:7], v[6:7], v[6:7]
	v_pk_mul_f32 v[8:9], v[2:3], v[2:3]
	v_pk_mul_f32 v[12:13], v[4:5], v[4:5]
	v_cvt_pk_bf16_f32 v2, v6, v7
	v_cvt_pk_bf16_f32 v3, v8, v9
	v_cvt_pk_bf16_f32 v4, v10, v11
	v_cvt_pk_bf16_f32 v5, v12, v13
	global_store_dwordx4 v[22:23], v[2:5], off offset:256
	s_cbranch_vccnz .LBB0_1227
	s_andn2_b64 vcc, exec, s[4:5]
	s_cbranch_vccnz .LBB0_1226
	s_barrier
	s_branch .LBB0_1226
